# FFN-in: leftover tiles split in halves, LDS-DMA issue interleaved with MFMAs, B tile double-buffered in LDS
# speedup vs baseline: 1.1177x; 1.0064x over previous
.Lfi_entry:
	v_and_b32_e32 v225, 63, v170
	v_lshrrev_b32_e32 v226, 6, v170
	v_and_b32_e32 v229, 15, v225
	v_lshrrev_b32_e32 v230, 4, v225
	v_lshlrev_b32_e32 v231, 10, v226
	v_lshrrev_b32_e32 v232, 3, v170
	v_readfirstlane_b32 s52, v231
	v_and_b32_e32 v233, 7, v170
	v_bfe_u32 v224, v232, 1, 3
	v_xor_b32_e32 v233, v233, v224
	v_lshlrev_b32_e32 v233, 4, v233
	s_movk_i32 s4, 0x880
	v_mad_u32_u24 v224, v232, s4, v233
	v_and_b32_e32 v233, 15, v232
	v_lshlrev_b32_e32 v233, 1, v233
	v_lshrrev_b32_e32 v168, 4, v232
	v_add_u32_e32 v233, v233, v168
	v_and_b32_e32 v168, 7, v170
	v_bfe_u32 v169, v232, 1, 3
	v_xor_b32_e32 v168, v168, v169
	v_lshlrev_b32_e32 v168, 4, v168
	v_mad_u32_u24 v168, v233, s4, v168
	v_bfe_u32 v233, v229, 1, 3
	v_xor_b32_e32 v231, v230, v233
	v_or_b32_e32 v232, 4, v230
	v_xor_b32_e32 v232, v232, v233
	v_lshlrev_b32_e32 v231, 4, v231
	v_lshlrev_b32_e32 v232, 4, v232
	v_lshrrev_b32_e32 v227, 1, v226
	v_and_b32_e32 v228, 1, v226
	v_lshl_add_u32 v233, v227, 7, v229
	v_lshlrev_b32_e32 v233, 7, v233
	v_add_u32_e32 v220, v233, v231
	v_add_u32_e32 v221, v233, v232
	v_lshl_add_u32 v233, v228, 6, v229
	v_lshlrev_b32_e32 v233, 7, v233
	v_add_u32_e32 v233, 0x8000, v233
	v_add_u32_e32 v222, v233, v231
	v_add_u32_e32 v223, v233, v232
	v_lshlrev_b32_e32 v233, 7, v227
	v_lshl_add_u32 v233, v230, 2, v233
	v_lshlrev_b32_e32 v227, 4, v228
	v_add_u32_e32 v227, v227, v229
	v_lshlrev_b32_e32 v227, 2, v227
	s_movk_i32 s4, 0x1680
	v_mad_u32_u24 v225, v233, s4, v227
	s_add_u32 s57, s52, 0x8000
	v_readlane_b32 s41, v235, 33
	s_mov_b32 s40, 2112
	s_cmp_lg_u32 s41, 0x200
	s_cbranch_scc1 .Lfi_nm
	s_mov_b32 s40, 2048
.Lfi_nm:
	s_nop 0
	v_writelane_b32 v239, s40, 0
	v_readlane_b32 s54, v237, 0
	s_cmp_ge_u32 s54, s40
	s_cbranch_scc1 .Lfi_main_done
	s_lshr_b32 s55, s54, 4
	s_mul_hi_u32 s55, s55, 0x55555556
	s_mul_i32 s53, s55, 48
	s_sub_u32 s53, s54, s53
	v_readlane_b32 s4, v235, 34
	v_readlane_b32 s5, v235, 35
	s_mul_i32 s44, s53, 0x88000
	s_add_u32 s44, s44, 0xe166000
	s_add_u32 s44, s44, s4
	s_addc_u32 s45, s5, 0
	s_mul_i32 s46, s55, 0x44000
	s_add_u32 s46, s46, s36
	s_addc_u32 s47, s37, 0
	s_lshr_b32 s55, s54, 4
	s_mul_hi_u32 s55, s55, 0x55555556
	s_mul_i32 s53, s55, 48
	s_sub_u32 s53, s54, s53
	v_readlane_b32 s4, v235, 34
	v_readlane_b32 s5, v235, 35
	s_mul_i32 s50, s53, 0x168000
	s_lshl_b32 s55, s55, 7
	s_add_u32 s50, s50, s55
	s_add_u32 s50, s50, 0xfae6000
	s_add_u32 s50, s50, s4
	s_addc_u32 s51, s5, 0
	s_add_u32 m0, s52, 0x0
	s_add_u32 s4, s44, 0x0
	s_addc_u32 s5, s45, 0
	global_load_lds_dwordx4 v224, s[4:5]
	s_add_u32 m0, s52, 0x1000
	s_add_u32 s4, s44, 0x11000
	s_addc_u32 s5, s45, 0
	global_load_lds_dwordx4 v224, s[4:5]
	s_add_u32 m0, s52, 0x2000
	s_add_u32 s4, s44, 0x22000
	s_addc_u32 s5, s45, 0
	global_load_lds_dwordx4 v224, s[4:5]
	s_add_u32 m0, s52, 0x3000
	s_add_u32 s4, s44, 0x33000
	s_addc_u32 s5, s45, 0
	global_load_lds_dwordx4 v224, s[4:5]
	s_add_u32 m0, s52, 0x4000
	s_add_u32 s4, s44, 0x44000
	s_addc_u32 s5, s45, 0
	global_load_lds_dwordx4 v224, s[4:5]
	s_add_u32 m0, s52, 0x5000
	s_add_u32 s4, s44, 0x55000
	s_addc_u32 s5, s45, 0
	global_load_lds_dwordx4 v224, s[4:5]
	s_add_u32 m0, s52, 0x6000
	s_add_u32 s4, s44, 0x66000
	s_addc_u32 s5, s45, 0
	global_load_lds_dwordx4 v224, s[4:5]
	s_add_u32 m0, s52, 0x7000
	s_add_u32 s4, s44, 0x77000
	s_addc_u32 s5, s45, 0
	global_load_lds_dwordx4 v224, s[4:5]
	s_add_u32 m0, s52, 0x8000
	s_add_u32 s4, s46, 0x0
	s_addc_u32 s5, s47, 0
	global_load_lds_dwordx4 v168, s[4:5]
	s_add_u32 m0, s52, 0x9000
	s_add_u32 s4, s46, 0x11000
	s_addc_u32 s5, s47, 0
	global_load_lds_dwordx4 v168, s[4:5]
	s_add_u32 m0, s52, 0xa000
	s_add_u32 s4, s46, 0x22000
	s_addc_u32 s5, s47, 0
	global_load_lds_dwordx4 v168, s[4:5]
	s_add_u32 m0, s52, 0xb000
	s_add_u32 s4, s46, 0x33000
	s_addc_u32 s5, s47, 0
	global_load_lds_dwordx4 v168, s[4:5]
	s_add_u32 s44, s44, 0x80
	s_addc_u32 s45, s45, 0
	s_add_u32 s46, s46, 0x80
	s_addc_u32 s47, s47, 0

.Lfi_k:
	s_waitcnt vmcnt(0)
	s_barrier
	s_cmp_eq_u32 s53, 15
	s_cbranch_scc1 .Lfi_nob
	s_xor_b32 s57, s57, 0x4000
	s_add_u32 m0, s57, 0x0
	s_add_u32 s4, s46, 0x0
	s_addc_u32 s5, s47, 0
	global_load_lds_dwordx4 v168, s[4:5]
	s_add_u32 m0, s57, 0x1000
	s_add_u32 s4, s46, 0x11000
	s_addc_u32 s5, s47, 0
	global_load_lds_dwordx4 v168, s[4:5]
	s_add_u32 m0, s57, 0x2000
	s_add_u32 s4, s46, 0x22000
	s_addc_u32 s5, s47, 0
	global_load_lds_dwordx4 v168, s[4:5]
	s_add_u32 m0, s57, 0x3000
	s_add_u32 s4, s46, 0x33000
	s_addc_u32 s5, s47, 0
	global_load_lds_dwordx4 v168, s[4:5]
	s_add_u32 s46, s46, 0x80
	s_addc_u32 s47, s47, 0
	s_branch .Lfi_nob2
.Lfi_nob:
	s_xor_b32 s57, s57, 0x4000
.Lfi_nob2:
	ds_read_b128 v[204:207], v222
	ds_read_b128 v[208:211], v222 offset:2048
	ds_read_b128 v[212:215], v222 offset:4096
	ds_read_b128 v[216:219], v222 offset:6144
	ds_read_b128 a[0:3], v223
	ds_read_b128 a[4:7], v223 offset:2048
	ds_read_b128 a[8:11], v223 offset:4096
	ds_read_b128 a[12:15], v223 offset:6144
	ds_read_b128 v[136:139], v220
	ds_read_b128 v[140:143], v220 offset:2048
	ds_read_b128 v[144:147], v220 offset:4096
	ds_read_b128 v[148:151], v220 offset:6144
	ds_read_b128 v[152:155], v220 offset:8192
	ds_read_b128 v[156:159], v220 offset:10240
	ds_read_b128 v[160:163], v220 offset:12288
	ds_read_b128 v[164:167], v220 offset:14336
	s_waitcnt lgkmcnt(7)
	v_mfma_f32_16x16x32_bf16 v[0:3], v[136:139], v[204:207], v[0:3]
	v_mfma_f32_16x16x32_bf16 v[4:7], v[136:139], v[208:211], v[4:7]
	v_mfma_f32_16x16x32_bf16 v[8:11], v[136:139], v[212:215], v[8:11]
	v_mfma_f32_16x16x32_bf16 v[12:15], v[136:139], v[216:219], v[12:15]
	ds_read_b128 v[136:139], v221
	s_waitcnt lgkmcnt(7)
	v_mfma_f32_16x16x32_bf16 v[16:19], v[140:143], v[204:207], v[16:19]
	v_mfma_f32_16x16x32_bf16 v[20:23], v[140:143], v[208:211], v[20:23]
	v_mfma_f32_16x16x32_bf16 v[24:27], v[140:143], v[212:215], v[24:27]
	v_mfma_f32_16x16x32_bf16 v[28:31], v[140:143], v[216:219], v[28:31]
	ds_read_b128 v[140:143], v221 offset:2048
	s_waitcnt lgkmcnt(7)
	v_mfma_f32_16x16x32_bf16 v[32:35], v[144:147], v[204:207], v[32:35]
	v_mfma_f32_16x16x32_bf16 v[36:39], v[144:147], v[208:211], v[36:39]
	v_mfma_f32_16x16x32_bf16 v[40:43], v[144:147], v[212:215], v[40:43]
	v_mfma_f32_16x16x32_bf16 v[44:47], v[144:147], v[216:219], v[44:47]
	ds_read_b128 v[144:147], v221 offset:4096
	s_waitcnt lgkmcnt(7)
	v_mfma_f32_16x16x32_bf16 v[48:51], v[148:151], v[204:207], v[48:51]
	v_mfma_f32_16x16x32_bf16 v[52:55], v[148:151], v[208:211], v[52:55]
	v_mfma_f32_16x16x32_bf16 v[56:59], v[148:151], v[212:215], v[56:59]
	v_mfma_f32_16x16x32_bf16 v[60:63], v[148:151], v[216:219], v[60:63]
	ds_read_b128 v[148:151], v221 offset:6144
	s_waitcnt lgkmcnt(7)
	v_mfma_f32_16x16x32_bf16 v[64:67], v[152:155], v[204:207], v[64:67]
	v_mfma_f32_16x16x32_bf16 v[68:71], v[152:155], v[208:211], v[68:71]
	v_mfma_f32_16x16x32_bf16 v[72:75], v[152:155], v[212:215], v[72:75]
	v_mfma_f32_16x16x32_bf16 v[76:79], v[152:155], v[216:219], v[76:79]
	ds_read_b128 v[152:155], v221 offset:8192
	s_waitcnt lgkmcnt(7)
	v_mfma_f32_16x16x32_bf16 v[80:83], v[156:159], v[204:207], v[80:83]
	v_mfma_f32_16x16x32_bf16 v[84:87], v[156:159], v[208:211], v[84:87]
	v_mfma_f32_16x16x32_bf16 v[88:91], v[156:159], v[212:215], v[88:91]
	v_mfma_f32_16x16x32_bf16 v[92:95], v[156:159], v[216:219], v[92:95]
	ds_read_b128 v[156:159], v221 offset:10240
	s_waitcnt lgkmcnt(7)
	v_mfma_f32_16x16x32_bf16 v[96:99], v[160:163], v[204:207], v[96:99]
	v_mfma_f32_16x16x32_bf16 v[100:103], v[160:163], v[208:211], v[100:103]
	v_mfma_f32_16x16x32_bf16 v[104:107], v[160:163], v[212:215], v[104:107]
	v_mfma_f32_16x16x32_bf16 v[108:111], v[160:163], v[216:219], v[108:111]
	ds_read_b128 v[160:163], v221 offset:12288
	s_waitcnt lgkmcnt(7)
	v_mfma_f32_16x16x32_bf16 v[112:115], v[164:167], v[204:207], v[112:115]
	v_mfma_f32_16x16x32_bf16 v[116:119], v[164:167], v[208:211], v[116:119]
	v_mfma_f32_16x16x32_bf16 v[120:123], v[164:167], v[212:215], v[120:123]
	v_mfma_f32_16x16x32_bf16 v[124:127], v[164:167], v[216:219], v[124:127]
	ds_read_b128 v[164:167], v221 offset:14336
	s_waitcnt lgkmcnt(0)
	s_barrier
	v_xor_b32_e32 v222, 0x4000, v222
	v_xor_b32_e32 v223, 0x4000, v223
	s_cmp_eq_u32 s53, 15
	s_cbranch_scc1 .Lfi_last
	v_mfma_f32_16x16x32_bf16 v[0:3], v[136:139], a[0:3], v[0:3]
	s_add_u32 m0, s52, 0x0
	s_add_u32 s4, s44, 0x0
	s_addc_u32 s5, s45, 0
	global_load_lds_dwordx4 v224, s[4:5]
	v_mfma_f32_16x16x32_bf16 v[4:7], v[136:139], a[4:7], v[4:7]
	v_mfma_f32_16x16x32_bf16 v[8:11], v[136:139], a[8:11], v[8:11]
	s_add_u32 m0, s52, 0x1000
	s_add_u32 s4, s44, 0x11000
	s_addc_u32 s5, s45, 0
	global_load_lds_dwordx4 v224, s[4:5]
	v_mfma_f32_16x16x32_bf16 v[12:15], v[136:139], a[12:15], v[12:15]
	v_mfma_f32_16x16x32_bf16 v[16:19], v[140:143], a[0:3], v[16:19]
	s_add_u32 m0, s52, 0x2000
	s_add_u32 s4, s44, 0x22000
	s_addc_u32 s5, s45, 0
	global_load_lds_dwordx4 v224, s[4:5]
	v_mfma_f32_16x16x32_bf16 v[20:23], v[140:143], a[4:7], v[20:23]
	v_mfma_f32_16x16x32_bf16 v[24:27], v[140:143], a[8:11], v[24:27]
	s_add_u32 m0, s52, 0x3000
	s_add_u32 s4, s44, 0x33000
	s_addc_u32 s5, s45, 0
	global_load_lds_dwordx4 v224, s[4:5]
	v_mfma_f32_16x16x32_bf16 v[28:31], v[140:143], a[12:15], v[28:31]
	v_mfma_f32_16x16x32_bf16 v[32:35], v[144:147], a[0:3], v[32:35]
	s_add_u32 m0, s52, 0x4000
	s_add_u32 s4, s44, 0x44000
	s_addc_u32 s5, s45, 0
	global_load_lds_dwordx4 v224, s[4:5]
	v_mfma_f32_16x16x32_bf16 v[36:39], v[144:147], a[4:7], v[36:39]
	v_mfma_f32_16x16x32_bf16 v[40:43], v[144:147], a[8:11], v[40:43]
	s_add_u32 m0, s52, 0x5000
	s_add_u32 s4, s44, 0x55000
	s_addc_u32 s5, s45, 0
	global_load_lds_dwordx4 v224, s[4:5]
	v_mfma_f32_16x16x32_bf16 v[44:47], v[144:147], a[12:15], v[44:47]
	v_mfma_f32_16x16x32_bf16 v[48:51], v[148:151], a[0:3], v[48:51]
	s_add_u32 m0, s52, 0x6000
	s_add_u32 s4, s44, 0x66000
	s_addc_u32 s5, s45, 0
	global_load_lds_dwordx4 v224, s[4:5]
	v_mfma_f32_16x16x32_bf16 v[52:55], v[148:151], a[4:7], v[52:55]
	v_mfma_f32_16x16x32_bf16 v[56:59], v[148:151], a[8:11], v[56:59]
	s_add_u32 m0, s52, 0x7000
	s_add_u32 s4, s44, 0x77000
	s_addc_u32 s5, s45, 0
	global_load_lds_dwordx4 v224, s[4:5]
	v_mfma_f32_16x16x32_bf16 v[60:63], v[148:151], a[12:15], v[60:63]
	v_mfma_f32_16x16x32_bf16 v[64:67], v[152:155], a[0:3], v[64:67]
	v_mfma_f32_16x16x32_bf16 v[68:71], v[152:155], a[4:7], v[68:71]
	v_mfma_f32_16x16x32_bf16 v[72:75], v[152:155], a[8:11], v[72:75]
	v_mfma_f32_16x16x32_bf16 v[76:79], v[152:155], a[12:15], v[76:79]
	v_mfma_f32_16x16x32_bf16 v[80:83], v[156:159], a[0:3], v[80:83]
	v_mfma_f32_16x16x32_bf16 v[84:87], v[156:159], a[4:7], v[84:87]
	v_mfma_f32_16x16x32_bf16 v[88:91], v[156:159], a[8:11], v[88:91]
	v_mfma_f32_16x16x32_bf16 v[92:95], v[156:159], a[12:15], v[92:95]
	v_mfma_f32_16x16x32_bf16 v[96:99], v[160:163], a[0:3], v[96:99]
	v_mfma_f32_16x16x32_bf16 v[100:103], v[160:163], a[4:7], v[100:103]
	v_mfma_f32_16x16x32_bf16 v[104:107], v[160:163], a[8:11], v[104:107]
	v_mfma_f32_16x16x32_bf16 v[108:111], v[160:163], a[12:15], v[108:111]
	v_mfma_f32_16x16x32_bf16 v[112:115], v[164:167], a[0:3], v[112:115]
	v_mfma_f32_16x16x32_bf16 v[116:119], v[164:167], a[4:7], v[116:119]
	v_mfma_f32_16x16x32_bf16 v[120:123], v[164:167], a[8:11], v[120:123]
	v_mfma_f32_16x16x32_bf16 v[124:127], v[164:167], a[12:15], v[124:127]
	s_add_u32 s44, s44, 0x80
	s_addc_u32 s45, s45, 0
	s_add_u32 s53, s53, 1
	s_branch .Lfi_k
.Lfi_last:
	v_readlane_b32 s55, v235, 33
	s_add_u32 s54, s54, s55
	v_readlane_b32 s40, v239, 0
	s_cmp_ge_u32 s54, s40
	s_cbranch_scc1 .Lfi_nopf
	s_lshr_b32 s55, s54, 4
	s_mul_hi_u32 s55, s55, 0x55555556
	s_mul_i32 s53, s55, 48
	s_sub_u32 s53, s54, s53
	v_readlane_b32 s4, v235, 34
	v_readlane_b32 s5, v235, 35
	s_mul_i32 s44, s53, 0x88000
	s_add_u32 s44, s44, 0xe166000
	s_add_u32 s44, s44, s4
	s_addc_u32 s45, s5, 0
	s_mul_i32 s46, s55, 0x44000
	s_add_u32 s46, s46, s36
	s_addc_u32 s47, s37, 0
	s_add_u32 m0, s52, 0x0
	s_add_u32 s4, s44, 0x0
	s_addc_u32 s5, s45, 0
	global_load_lds_dwordx4 v224, s[4:5]
	s_add_u32 m0, s52, 0x1000
	s_add_u32 s4, s44, 0x11000
	s_addc_u32 s5, s45, 0
	global_load_lds_dwordx4 v224, s[4:5]
	s_add_u32 m0, s52, 0x2000
	s_add_u32 s4, s44, 0x22000
	s_addc_u32 s5, s45, 0
	global_load_lds_dwordx4 v224, s[4:5]
	s_add_u32 m0, s52, 0x3000
	s_add_u32 s4, s44, 0x33000
	s_addc_u32 s5, s45, 0
	global_load_lds_dwordx4 v224, s[4:5]
	s_add_u32 m0, s52, 0x4000
	s_add_u32 s4, s44, 0x44000
	s_addc_u32 s5, s45, 0
	global_load_lds_dwordx4 v224, s[4:5]
	s_add_u32 m0, s52, 0x5000
	s_add_u32 s4, s44, 0x55000
	s_addc_u32 s5, s45, 0
	global_load_lds_dwordx4 v224, s[4:5]
	s_add_u32 m0, s52, 0x6000
	s_add_u32 s4, s44, 0x66000
	s_addc_u32 s5, s45, 0
	global_load_lds_dwordx4 v224, s[4:5]
	s_add_u32 m0, s52, 0x7000
	s_add_u32 s4, s44, 0x77000
	s_addc_u32 s5, s45, 0
	global_load_lds_dwordx4 v224, s[4:5]
	s_add_u32 m0, s52, 0x8000
	s_add_u32 s4, s46, 0x0
	s_addc_u32 s5, s47, 0
	global_load_lds_dwordx4 v168, s[4:5]
	s_add_u32 m0, s52, 0x9000
	s_add_u32 s4, s46, 0x11000
	s_addc_u32 s5, s47, 0
	global_load_lds_dwordx4 v168, s[4:5]
	s_add_u32 m0, s52, 0xa000
	s_add_u32 s4, s46, 0x22000
	s_addc_u32 s5, s47, 0
	global_load_lds_dwordx4 v168, s[4:5]
	s_add_u32 m0, s52, 0xb000
	s_add_u32 s4, s46, 0x33000
	s_addc_u32 s5, s47, 0
	global_load_lds_dwordx4 v168, s[4:5]
	s_add_u32 s44, s44, 0x80
	s_addc_u32 s45, s45, 0
	s_add_u32 s46, s46, 0x80
	s_addc_u32 s47, s47, 0
.Lfi_nopf:
	v_mfma_f32_16x16x32_bf16 v[0:3], v[136:139], a[0:3], v[0:3]
	v_mfma_f32_16x16x32_bf16 v[4:7], v[136:139], a[4:7], v[4:7]
	v_mfma_f32_16x16x32_bf16 v[8:11], v[136:139], a[8:11], v[8:11]
	v_mfma_f32_16x16x32_bf16 v[12:15], v[136:139], a[12:15], v[12:15]
	v_mfma_f32_16x16x32_bf16 v[16:19], v[140:143], a[0:3], v[16:19]
	v_mfma_f32_16x16x32_bf16 v[20:23], v[140:143], a[4:7], v[20:23]
	v_mfma_f32_16x16x32_bf16 v[24:27], v[140:143], a[8:11], v[24:27]
	v_mfma_f32_16x16x32_bf16 v[28:31], v[140:143], a[12:15], v[28:31]
	v_mfma_f32_16x16x32_bf16 v[32:35], v[144:147], a[0:3], v[32:35]
	v_mfma_f32_16x16x32_bf16 v[36:39], v[144:147], a[4:7], v[36:39]
	v_mfma_f32_16x16x32_bf16 v[40:43], v[144:147], a[8:11], v[40:43]
	v_mfma_f32_16x16x32_bf16 v[44:47], v[144:147], a[12:15], v[44:47]
	v_mfma_f32_16x16x32_bf16 v[48:51], v[148:151], a[0:3], v[48:51]
	v_mfma_f32_16x16x32_bf16 v[52:55], v[148:151], a[4:7], v[52:55]
	v_mfma_f32_16x16x32_bf16 v[56:59], v[148:151], a[8:11], v[56:59]
	v_mfma_f32_16x16x32_bf16 v[60:63], v[148:151], a[12:15], v[60:63]
	v_mfma_f32_16x16x32_bf16 v[64:67], v[152:155], a[0:3], v[64:67]
	v_mfma_f32_16x16x32_bf16 v[68:71], v[152:155], a[4:7], v[68:71]
	v_mfma_f32_16x16x32_bf16 v[72:75], v[152:155], a[8:11], v[72:75]
	v_mfma_f32_16x16x32_bf16 v[76:79], v[152:155], a[12:15], v[76:79]
	v_mfma_f32_16x16x32_bf16 v[80:83], v[156:159], a[0:3], v[80:83]
	v_mfma_f32_16x16x32_bf16 v[84:87], v[156:159], a[4:7], v[84:87]
	v_mfma_f32_16x16x32_bf16 v[88:91], v[156:159], a[8:11], v[88:91]
	v_mfma_f32_16x16x32_bf16 v[92:95], v[156:159], a[12:15], v[92:95]
	v_mfma_f32_16x16x32_bf16 v[96:99], v[160:163], a[0:3], v[96:99]
	v_mfma_f32_16x16x32_bf16 v[100:103], v[160:163], a[4:7], v[100:103]
	v_mfma_f32_16x16x32_bf16 v[104:107], v[160:163], a[8:11], v[104:107]
	v_mfma_f32_16x16x32_bf16 v[108:111], v[160:163], a[12:15], v[108:111]
	v_mfma_f32_16x16x32_bf16 v[112:115], v[164:167], a[0:3], v[112:115]
	v_mfma_f32_16x16x32_bf16 v[116:119], v[164:167], a[4:7], v[116:119]
	v_mfma_f32_16x16x32_bf16 v[120:123], v[164:167], a[8:11], v[120:123]
	v_mfma_f32_16x16x32_bf16 v[124:127], v[164:167], a[12:15], v[124:127]
	s_nop 7
	s_nop 7
	v_mov_b32_e32 v226, s50
	v_mov_b32_e32 v227, s51
	v_add_co_u32_e32 v226, vcc, v226, v225
	s_nop 1
	v_addc_co_u32_e32 v227, vcc, 0, v227, vcc
	v_mul_f32_e32 v228, 0xbfb8aa3b, v0
	v_exp_f32_e32 v228, v228
	s_nop 0
	v_add_f32_e32 v229, 1.0, v228
	v_div_scale_f32 v230, s[4:5], v229, v229, v0
	v_rcp_f32_e32 v231, v230
	v_div_scale_f32 v232, vcc, v0, v229, v0
	v_fma_f32 v131, -v230, v231, 1.0
	v_fmac_f32_e32 v231, v131, v231
	v_mul_f32_e32 v233, v232, v231
	v_fma_f32 v131, -v230, v233, v232
	v_fmac_f32_e32 v233, v131, v231
	v_fma_f32 v230, -v230, v233, v232
	v_div_fmas_f32 v230, v230, v231, v233
	v_div_fixup_f32 v135, v230, v229, v0
	v_mul_f32_e32 v135, v8, v135
	v_mul_f32_e32 v228, 0xbfb8aa3b, v4
	v_exp_f32_e32 v228, v228
	s_nop 0
	v_add_f32_e32 v229, 1.0, v228
	v_div_scale_f32 v230, s[4:5], v229, v229, v4
	v_rcp_f32_e32 v231, v230
	v_div_scale_f32 v232, vcc, v4, v229, v4
	v_fma_f32 v131, -v230, v231, 1.0
	v_fmac_f32_e32 v231, v131, v231
	v_mul_f32_e32 v233, v232, v231
	v_fma_f32 v131, -v230, v233, v232
	v_fmac_f32_e32 v233, v131, v231
	v_fma_f32 v230, -v230, v233, v232
	v_div_fmas_f32 v230, v230, v231, v233
	v_div_fixup_f32 v133, v230, v229, v4
	v_mul_f32_e32 v133, v12, v133
	v_cvt_pk_bf16_f32 v133, v135, v133
	global_store_dword v[226:227], v133, off
	s_mov_b64 s[40:41], 0x1680
	v_lshl_add_u64 v[226:227], v[226:227], 0, s[40:41]
	v_mul_f32_e32 v228, 0xbfb8aa3b, v1
	v_exp_f32_e32 v228, v228
	s_nop 0
	v_add_f32_e32 v229, 1.0, v228
	v_div_scale_f32 v230, s[4:5], v229, v229, v1
	v_rcp_f32_e32 v231, v230
	v_div_scale_f32 v232, vcc, v1, v229, v1
	v_fma_f32 v131, -v230, v231, 1.0
	v_fmac_f32_e32 v231, v131, v231
	v_mul_f32_e32 v233, v232, v231
	v_fma_f32 v131, -v230, v233, v232
	v_fmac_f32_e32 v233, v131, v231
	v_fma_f32 v230, -v230, v233, v232
	v_div_fmas_f32 v230, v230, v231, v233
	v_div_fixup_f32 v135, v230, v229, v1
	v_mul_f32_e32 v135, v9, v135
	v_mul_f32_e32 v228, 0xbfb8aa3b, v5
	v_exp_f32_e32 v228, v228
	s_nop 0
	v_add_f32_e32 v229, 1.0, v228
	v_div_scale_f32 v230, s[4:5], v229, v229, v5
	v_rcp_f32_e32 v231, v230
	v_div_scale_f32 v232, vcc, v5, v229, v5
	v_fma_f32 v131, -v230, v231, 1.0
	v_fmac_f32_e32 v231, v131, v231
	v_mul_f32_e32 v233, v232, v231
	v_fma_f32 v131, -v230, v233, v232
	v_fmac_f32_e32 v233, v131, v231
	v_fma_f32 v230, -v230, v233, v232
	v_div_fmas_f32 v230, v230, v231, v233
	v_div_fixup_f32 v133, v230, v229, v5
	v_mul_f32_e32 v133, v13, v133
	v_cvt_pk_bf16_f32 v133, v135, v133
	global_store_dword v[226:227], v133, off
	s_mov_b64 s[40:41], 0x1680
	v_lshl_add_u64 v[226:227], v[226:227], 0, s[40:41]
	v_mul_f32_e32 v228, 0xbfb8aa3b, v2
	v_exp_f32_e32 v228, v228
	s_nop 0
	v_add_f32_e32 v229, 1.0, v228
	v_div_scale_f32 v230, s[4:5], v229, v229, v2
	v_rcp_f32_e32 v231, v230
	v_div_scale_f32 v232, vcc, v2, v229, v2
	v_fma_f32 v131, -v230, v231, 1.0
	v_fmac_f32_e32 v231, v131, v231
	v_mul_f32_e32 v233, v232, v231
	v_fma_f32 v131, -v230, v233, v232
	v_fmac_f32_e32 v233, v131, v231
	v_fma_f32 v230, -v230, v233, v232
	v_div_fmas_f32 v230, v230, v231, v233
	v_div_fixup_f32 v135, v230, v229, v2
	v_mul_f32_e32 v135, v10, v135
	v_mul_f32_e32 v228, 0xbfb8aa3b, v6
	v_exp_f32_e32 v228, v228
	s_nop 0
	v_add_f32_e32 v229, 1.0, v228
	v_div_scale_f32 v230, s[4:5], v229, v229, v6
	v_rcp_f32_e32 v231, v230
	v_div_scale_f32 v232, vcc, v6, v229, v6
	v_fma_f32 v131, -v230, v231, 1.0
	v_fmac_f32_e32 v231, v131, v231
	v_mul_f32_e32 v233, v232, v231
	v_fma_f32 v131, -v230, v233, v232
	v_fmac_f32_e32 v233, v131, v231
	v_fma_f32 v230, -v230, v233, v232
	v_div_fmas_f32 v230, v230, v231, v233
	v_div_fixup_f32 v133, v230, v229, v6
	v_mul_f32_e32 v133, v14, v133
	v_cvt_pk_bf16_f32 v133, v135, v133
	global_store_dword v[226:227], v133, off
	s_mov_b64 s[40:41], 0x1680
	v_lshl_add_u64 v[226:227], v[226:227], 0, s[40:41]
	v_mul_f32_e32 v228, 0xbfb8aa3b, v3
	v_exp_f32_e32 v228, v228
	s_nop 0
	v_add_f32_e32 v229, 1.0, v228
	v_div_scale_f32 v230, s[4:5], v229, v229, v3
	v_rcp_f32_e32 v231, v230
	v_div_scale_f32 v232, vcc, v3, v229, v3
	v_fma_f32 v131, -v230, v231, 1.0
	v_fmac_f32_e32 v231, v131, v231
	v_mul_f32_e32 v233, v232, v231
	v_fma_f32 v131, -v230, v233, v232
	v_fmac_f32_e32 v233, v131, v231
	v_fma_f32 v230, -v230, v233, v232
	v_div_fmas_f32 v230, v230, v231, v233
	v_div_fixup_f32 v135, v230, v229, v3
	v_mul_f32_e32 v135, v11, v135
	v_mul_f32_e32 v228, 0xbfb8aa3b, v7
	v_exp_f32_e32 v228, v228
	s_nop 0
	v_add_f32_e32 v229, 1.0, v228
	v_div_scale_f32 v230, s[4:5], v229, v229, v7
	v_rcp_f32_e32 v231, v230
	v_div_scale_f32 v232, vcc, v7, v229, v7
	v_fma_f32 v131, -v230, v231, 1.0
	v_fmac_f32_e32 v231, v131, v231
	v_mul_f32_e32 v233, v232, v231
	v_fma_f32 v131, -v230, v233, v232
	v_fmac_f32_e32 v233, v131, v231
	v_fma_f32 v230, -v230, v233, v232
	v_div_fmas_f32 v230, v230, v231, v233
	v_div_fixup_f32 v133, v230, v229, v7
	v_mul_f32_e32 v133, v15, v133
	v_cvt_pk_bf16_f32 v133, v135, v133
	global_store_dword v[226:227], v133, off
	s_mov_b64 s[40:41], 0x12480
	v_lshl_add_u64 v[226:227], v[226:227], 0, s[40:41]
	v_mul_f32_e32 v228, 0xbfb8aa3b, v16
	v_exp_f32_e32 v228, v228
	s_nop 0
	v_add_f32_e32 v229, 1.0, v228
	v_div_scale_f32 v230, s[4:5], v229, v229, v16
	v_rcp_f32_e32 v231, v230
	v_div_scale_f32 v232, vcc, v16, v229, v16
	v_fma_f32 v131, -v230, v231, 1.0
	v_fmac_f32_e32 v231, v131, v231
	v_mul_f32_e32 v233, v232, v231
	v_fma_f32 v131, -v230, v233, v232
	v_fmac_f32_e32 v233, v131, v231
	v_fma_f32 v230, -v230, v233, v232
	v_div_fmas_f32 v230, v230, v231, v233
	v_div_fixup_f32 v135, v230, v229, v16
	v_mul_f32_e32 v135, v24, v135
	v_mul_f32_e32 v228, 0xbfb8aa3b, v20
	v_exp_f32_e32 v228, v228
	s_nop 0
	v_add_f32_e32 v229, 1.0, v228
	v_div_scale_f32 v230, s[4:5], v229, v229, v20
	v_rcp_f32_e32 v231, v230
	v_div_scale_f32 v232, vcc, v20, v229, v20
	v_fma_f32 v131, -v230, v231, 1.0
	v_fmac_f32_e32 v231, v131, v231
	v_mul_f32_e32 v233, v232, v231
	v_fma_f32 v131, -v230, v233, v232
	v_fmac_f32_e32 v233, v131, v231
	v_fma_f32 v230, -v230, v233, v232
	v_div_fmas_f32 v230, v230, v231, v233
	v_div_fixup_f32 v133, v230, v229, v20
	v_mul_f32_e32 v133, v28, v133
	v_cvt_pk_bf16_f32 v133, v135, v133
	global_store_dword v[226:227], v133, off
	s_mov_b64 s[40:41], 0x1680
	v_lshl_add_u64 v[226:227], v[226:227], 0, s[40:41]
	v_mul_f32_e32 v228, 0xbfb8aa3b, v17
	v_exp_f32_e32 v228, v228
	s_nop 0
	v_add_f32_e32 v229, 1.0, v228
	v_div_scale_f32 v230, s[4:5], v229, v229, v17
	v_rcp_f32_e32 v231, v230
	v_div_scale_f32 v232, vcc, v17, v229, v17
	v_fma_f32 v131, -v230, v231, 1.0
	v_fmac_f32_e32 v231, v131, v231
	v_mul_f32_e32 v233, v232, v231
	v_fma_f32 v131, -v230, v233, v232
	v_fmac_f32_e32 v233, v131, v231
	v_fma_f32 v230, -v230, v233, v232
	v_div_fmas_f32 v230, v230, v231, v233
	v_div_fixup_f32 v135, v230, v229, v17
	v_mul_f32_e32 v135, v25, v135
	v_mul_f32_e32 v228, 0xbfb8aa3b, v21
	v_exp_f32_e32 v228, v228
	s_nop 0
	v_add_f32_e32 v229, 1.0, v228
	v_div_scale_f32 v230, s[4:5], v229, v229, v21
	v_rcp_f32_e32 v231, v230
	v_div_scale_f32 v232, vcc, v21, v229, v21
	v_fma_f32 v131, -v230, v231, 1.0
	v_fmac_f32_e32 v231, v131, v231
	v_mul_f32_e32 v233, v232, v231
	v_fma_f32 v131, -v230, v233, v232
	v_fmac_f32_e32 v233, v131, v231
	v_fma_f32 v230, -v230, v233, v232
	v_div_fmas_f32 v230, v230, v231, v233
	v_div_fixup_f32 v133, v230, v229, v21
	v_mul_f32_e32 v133, v29, v133
	v_cvt_pk_bf16_f32 v133, v135, v133
	global_store_dword v[226:227], v133, off
	s_mov_b64 s[40:41], 0x1680
	v_lshl_add_u64 v[226:227], v[226:227], 0, s[40:41]
	v_mul_f32_e32 v228, 0xbfb8aa3b, v18
	v_exp_f32_e32 v228, v228
	s_nop 0
	v_add_f32_e32 v229, 1.0, v228
	v_div_scale_f32 v230, s[4:5], v229, v229, v18
	v_rcp_f32_e32 v231, v230
	v_div_scale_f32 v232, vcc, v18, v229, v18
	v_fma_f32 v131, -v230, v231, 1.0
	v_fmac_f32_e32 v231, v131, v231
	v_mul_f32_e32 v233, v232, v231
	v_fma_f32 v131, -v230, v233, v232
	v_fmac_f32_e32 v233, v131, v231
	v_fma_f32 v230, -v230, v233, v232
	v_div_fmas_f32 v230, v230, v231, v233
	v_div_fixup_f32 v135, v230, v229, v18
	v_mul_f32_e32 v135, v26, v135
	v_mul_f32_e32 v228, 0xbfb8aa3b, v22
	v_exp_f32_e32 v228, v228
	s_nop 0
	v_add_f32_e32 v229, 1.0, v228
	v_div_scale_f32 v230, s[4:5], v229, v229, v22
	v_rcp_f32_e32 v231, v230
	v_div_scale_f32 v232, vcc, v22, v229, v22
	v_fma_f32 v131, -v230, v231, 1.0
	v_fmac_f32_e32 v231, v131, v231
	v_mul_f32_e32 v233, v232, v231
	v_fma_f32 v131, -v230, v233, v232
	v_fmac_f32_e32 v233, v131, v231
	v_fma_f32 v230, -v230, v233, v232
	v_div_fmas_f32 v230, v230, v231, v233
	v_div_fixup_f32 v133, v230, v229, v22
	v_mul_f32_e32 v133, v30, v133
	v_cvt_pk_bf16_f32 v133, v135, v133
	global_store_dword v[226:227], v133, off
	s_mov_b64 s[40:41], 0x1680
	v_lshl_add_u64 v[226:227], v[226:227], 0, s[40:41]
	v_mul_f32_e32 v228, 0xbfb8aa3b, v19
	v_exp_f32_e32 v228, v228
	s_nop 0
	v_add_f32_e32 v229, 1.0, v228
	v_div_scale_f32 v230, s[4:5], v229, v229, v19
	v_rcp_f32_e32 v231, v230
	v_div_scale_f32 v232, vcc, v19, v229, v19
	v_fma_f32 v131, -v230, v231, 1.0
	v_fmac_f32_e32 v231, v131, v231
	v_mul_f32_e32 v233, v232, v231
	v_fma_f32 v131, -v230, v233, v232
	v_fmac_f32_e32 v233, v131, v231
	v_fma_f32 v230, -v230, v233, v232
	v_div_fmas_f32 v230, v230, v231, v233
	v_div_fixup_f32 v135, v230, v229, v19
	v_mul_f32_e32 v135, v27, v135
	v_mul_f32_e32 v228, 0xbfb8aa3b, v23
	v_exp_f32_e32 v228, v228
	s_nop 0
	v_add_f32_e32 v229, 1.0, v228
	v_div_scale_f32 v230, s[4:5], v229, v229, v23
	v_rcp_f32_e32 v231, v230
	v_div_scale_f32 v232, vcc, v23, v229, v23
	v_fma_f32 v131, -v230, v231, 1.0
	v_fmac_f32_e32 v231, v131, v231
	v_mul_f32_e32 v233, v232, v231
	v_fma_f32 v131, -v230, v233, v232
	v_fmac_f32_e32 v233, v131, v231
	v_fma_f32 v230, -v230, v233, v232
	v_div_fmas_f32 v230, v230, v231, v233
	v_div_fixup_f32 v133, v230, v229, v23
	v_mul_f32_e32 v133, v31, v133
	v_cvt_pk_bf16_f32 v133, v135, v133
	global_store_dword v[226:227], v133, off
	s_mov_b64 s[40:41], 0x12480
	v_lshl_add_u64 v[226:227], v[226:227], 0, s[40:41]
	v_mul_f32_e32 v228, 0xbfb8aa3b, v32
	v_exp_f32_e32 v228, v228
	s_nop 0
	v_add_f32_e32 v229, 1.0, v228
	v_div_scale_f32 v230, s[4:5], v229, v229, v32
	v_rcp_f32_e32 v231, v230
	v_div_scale_f32 v232, vcc, v32, v229, v32
	v_fma_f32 v131, -v230, v231, 1.0
	v_fmac_f32_e32 v231, v131, v231
	v_mul_f32_e32 v233, v232, v231
	v_fma_f32 v131, -v230, v233, v232
	v_fmac_f32_e32 v233, v131, v231
	v_fma_f32 v230, -v230, v233, v232
	v_div_fmas_f32 v230, v230, v231, v233
	v_div_fixup_f32 v135, v230, v229, v32
	v_mul_f32_e32 v135, v40, v135
	v_mul_f32_e32 v228, 0xbfb8aa3b, v36
	v_exp_f32_e32 v228, v228
	s_nop 0
	v_add_f32_e32 v229, 1.0, v228
	v_div_scale_f32 v230, s[4:5], v229, v229, v36
	v_rcp_f32_e32 v231, v230
	v_div_scale_f32 v232, vcc, v36, v229, v36
	v_fma_f32 v131, -v230, v231, 1.0
	v_fmac_f32_e32 v231, v131, v231
	v_mul_f32_e32 v233, v232, v231
	v_fma_f32 v131, -v230, v233, v232
	v_fmac_f32_e32 v233, v131, v231
	v_fma_f32 v230, -v230, v233, v232
	v_div_fmas_f32 v230, v230, v231, v233
	v_div_fixup_f32 v133, v230, v229, v36
	v_mul_f32_e32 v133, v44, v133
	v_cvt_pk_bf16_f32 v133, v135, v133
	global_store_dword v[226:227], v133, off
	s_mov_b64 s[40:41], 0x1680
	v_lshl_add_u64 v[226:227], v[226:227], 0, s[40:41]
	v_mul_f32_e32 v228, 0xbfb8aa3b, v33
	v_exp_f32_e32 v228, v228
	s_nop 0
	v_add_f32_e32 v229, 1.0, v228
	v_div_scale_f32 v230, s[4:5], v229, v229, v33
	v_rcp_f32_e32 v231, v230
	v_div_scale_f32 v232, vcc, v33, v229, v33
	v_fma_f32 v131, -v230, v231, 1.0
	v_fmac_f32_e32 v231, v131, v231
	v_mul_f32_e32 v233, v232, v231
	v_fma_f32 v131, -v230, v233, v232
	v_fmac_f32_e32 v233, v131, v231
	v_fma_f32 v230, -v230, v233, v232
	v_div_fmas_f32 v230, v230, v231, v233
	v_div_fixup_f32 v135, v230, v229, v33
	v_mul_f32_e32 v135, v41, v135
	v_mul_f32_e32 v228, 0xbfb8aa3b, v37
	v_exp_f32_e32 v228, v228
	s_nop 0
	v_add_f32_e32 v229, 1.0, v228
	v_div_scale_f32 v230, s[4:5], v229, v229, v37
	v_rcp_f32_e32 v231, v230
	v_div_scale_f32 v232, vcc, v37, v229, v37
	v_fma_f32 v131, -v230, v231, 1.0
	v_fmac_f32_e32 v231, v131, v231
	v_mul_f32_e32 v233, v232, v231
	v_fma_f32 v131, -v230, v233, v232
	v_fmac_f32_e32 v233, v131, v231
	v_fma_f32 v230, -v230, v233, v232
	v_div_fmas_f32 v230, v230, v231, v233
	v_div_fixup_f32 v133, v230, v229, v37
	v_mul_f32_e32 v133, v45, v133
	v_cvt_pk_bf16_f32 v133, v135, v133
	global_store_dword v[226:227], v133, off
	s_mov_b64 s[40:41], 0x1680
	v_lshl_add_u64 v[226:227], v[226:227], 0, s[40:41]
	v_mul_f32_e32 v228, 0xbfb8aa3b, v34
	v_exp_f32_e32 v228, v228
	s_nop 0
	v_add_f32_e32 v229, 1.0, v228
	v_div_scale_f32 v230, s[4:5], v229, v229, v34
	v_rcp_f32_e32 v231, v230
	v_div_scale_f32 v232, vcc, v34, v229, v34
	v_fma_f32 v131, -v230, v231, 1.0
	v_fmac_f32_e32 v231, v131, v231
	v_mul_f32_e32 v233, v232, v231
	v_fma_f32 v131, -v230, v233, v232
	v_fmac_f32_e32 v233, v131, v231
	v_fma_f32 v230, -v230, v233, v232
	v_div_fmas_f32 v230, v230, v231, v233
	v_div_fixup_f32 v135, v230, v229, v34
	v_mul_f32_e32 v135, v42, v135
	v_mul_f32_e32 v228, 0xbfb8aa3b, v38
	v_exp_f32_e32 v228, v228
	s_nop 0
	v_add_f32_e32 v229, 1.0, v228
	v_div_scale_f32 v230, s[4:5], v229, v229, v38
	v_rcp_f32_e32 v231, v230
	v_div_scale_f32 v232, vcc, v38, v229, v38
	v_fma_f32 v131, -v230, v231, 1.0
	v_fmac_f32_e32 v231, v131, v231
	v_mul_f32_e32 v233, v232, v231
	v_fma_f32 v131, -v230, v233, v232
	v_fmac_f32_e32 v233, v131, v231
	v_fma_f32 v230, -v230, v233, v232
	v_div_fmas_f32 v230, v230, v231, v233
	v_div_fixup_f32 v133, v230, v229, v38
	v_mul_f32_e32 v133, v46, v133
	v_cvt_pk_bf16_f32 v133, v135, v133
	global_store_dword v[226:227], v133, off
	s_mov_b64 s[40:41], 0x1680
	v_lshl_add_u64 v[226:227], v[226:227], 0, s[40:41]
	v_mul_f32_e32 v228, 0xbfb8aa3b, v35
	v_exp_f32_e32 v228, v228
	s_nop 0
	v_add_f32_e32 v229, 1.0, v228
	v_div_scale_f32 v230, s[4:5], v229, v229, v35
	v_rcp_f32_e32 v231, v230
	v_div_scale_f32 v232, vcc, v35, v229, v35
	v_fma_f32 v131, -v230, v231, 1.0
	v_fmac_f32_e32 v231, v131, v231
	v_mul_f32_e32 v233, v232, v231
	v_fma_f32 v131, -v230, v233, v232
	v_fmac_f32_e32 v233, v131, v231
	v_fma_f32 v230, -v230, v233, v232
	v_div_fmas_f32 v230, v230, v231, v233
	v_div_fixup_f32 v135, v230, v229, v35
	v_mul_f32_e32 v135, v43, v135
	v_mul_f32_e32 v228, 0xbfb8aa3b, v39
	v_exp_f32_e32 v228, v228
	s_nop 0
	v_add_f32_e32 v229, 1.0, v228
	v_div_scale_f32 v230, s[4:5], v229, v229, v39
	v_rcp_f32_e32 v231, v230
	v_div_scale_f32 v232, vcc, v39, v229, v39
	v_fma_f32 v131, -v230, v231, 1.0
	v_fmac_f32_e32 v231, v131, v231
	v_mul_f32_e32 v233, v232, v231
	v_fma_f32 v131, -v230, v233, v232
	v_fmac_f32_e32 v233, v131, v231
	v_fma_f32 v230, -v230, v233, v232
	v_div_fmas_f32 v230, v230, v231, v233
	v_div_fixup_f32 v133, v230, v229, v39
	v_mul_f32_e32 v133, v47, v133
	v_cvt_pk_bf16_f32 v133, v135, v133
	global_store_dword v[226:227], v133, off
	s_mov_b64 s[40:41], 0x12480
	v_lshl_add_u64 v[226:227], v[226:227], 0, s[40:41]
	v_mul_f32_e32 v228, 0xbfb8aa3b, v48
	v_exp_f32_e32 v228, v228
	s_nop 0
	v_add_f32_e32 v229, 1.0, v228
	v_div_scale_f32 v230, s[4:5], v229, v229, v48
	v_rcp_f32_e32 v231, v230
	v_div_scale_f32 v232, vcc, v48, v229, v48
	v_fma_f32 v131, -v230, v231, 1.0
	v_fmac_f32_e32 v231, v131, v231
	v_mul_f32_e32 v233, v232, v231
	v_fma_f32 v131, -v230, v233, v232
	v_fmac_f32_e32 v233, v131, v231
	v_fma_f32 v230, -v230, v233, v232
	v_div_fmas_f32 v230, v230, v231, v233
	v_div_fixup_f32 v135, v230, v229, v48
	v_mul_f32_e32 v135, v56, v135
	v_mul_f32_e32 v228, 0xbfb8aa3b, v52
	v_exp_f32_e32 v228, v228
	s_nop 0
	v_add_f32_e32 v229, 1.0, v228
	v_div_scale_f32 v230, s[4:5], v229, v229, v52
	v_rcp_f32_e32 v231, v230
	v_div_scale_f32 v232, vcc, v52, v229, v52
	v_fma_f32 v131, -v230, v231, 1.0
	v_fmac_f32_e32 v231, v131, v231
	v_mul_f32_e32 v233, v232, v231
	v_fma_f32 v131, -v230, v233, v232
	v_fmac_f32_e32 v233, v131, v231
	v_fma_f32 v230, -v230, v233, v232
	v_div_fmas_f32 v230, v230, v231, v233
	v_div_fixup_f32 v133, v230, v229, v52
	v_mul_f32_e32 v133, v60, v133
	v_cvt_pk_bf16_f32 v133, v135, v133
	global_store_dword v[226:227], v133, off
	s_mov_b64 s[40:41], 0x1680
	v_lshl_add_u64 v[226:227], v[226:227], 0, s[40:41]
	v_mul_f32_e32 v228, 0xbfb8aa3b, v49
	v_exp_f32_e32 v228, v228
	s_nop 0
	v_add_f32_e32 v229, 1.0, v228
	v_div_scale_f32 v230, s[4:5], v229, v229, v49
	v_rcp_f32_e32 v231, v230
	v_div_scale_f32 v232, vcc, v49, v229, v49
	v_fma_f32 v131, -v230, v231, 1.0
	v_fmac_f32_e32 v231, v131, v231
	v_mul_f32_e32 v233, v232, v231
	v_fma_f32 v131, -v230, v233, v232
	v_fmac_f32_e32 v233, v131, v231
	v_fma_f32 v230, -v230, v233, v232
	v_div_fmas_f32 v230, v230, v231, v233
	v_div_fixup_f32 v135, v230, v229, v49
	v_mul_f32_e32 v135, v57, v135
	v_mul_f32_e32 v228, 0xbfb8aa3b, v53
	v_exp_f32_e32 v228, v228
	s_nop 0
	v_add_f32_e32 v229, 1.0, v228
	v_div_scale_f32 v230, s[4:5], v229, v229, v53
	v_rcp_f32_e32 v231, v230
	v_div_scale_f32 v232, vcc, v53, v229, v53
	v_fma_f32 v131, -v230, v231, 1.0
	v_fmac_f32_e32 v231, v131, v231
	v_mul_f32_e32 v233, v232, v231
	v_fma_f32 v131, -v230, v233, v232
	v_fmac_f32_e32 v233, v131, v231
	v_fma_f32 v230, -v230, v233, v232
	v_div_fmas_f32 v230, v230, v231, v233
	v_div_fixup_f32 v133, v230, v229, v53
	v_mul_f32_e32 v133, v61, v133
	v_cvt_pk_bf16_f32 v133, v135, v133
	global_store_dword v[226:227], v133, off
	s_mov_b64 s[40:41], 0x1680
	v_lshl_add_u64 v[226:227], v[226:227], 0, s[40:41]
	v_mul_f32_e32 v228, 0xbfb8aa3b, v50
	v_exp_f32_e32 v228, v228
	s_nop 0
	v_add_f32_e32 v229, 1.0, v228
	v_div_scale_f32 v230, s[4:5], v229, v229, v50
	v_rcp_f32_e32 v231, v230
	v_div_scale_f32 v232, vcc, v50, v229, v50
	v_fma_f32 v131, -v230, v231, 1.0
	v_fmac_f32_e32 v231, v131, v231
	v_mul_f32_e32 v233, v232, v231
	v_fma_f32 v131, -v230, v233, v232
	v_fmac_f32_e32 v233, v131, v231
	v_fma_f32 v230, -v230, v233, v232
	v_div_fmas_f32 v230, v230, v231, v233
	v_div_fixup_f32 v135, v230, v229, v50
	v_mul_f32_e32 v135, v58, v135
	v_mul_f32_e32 v228, 0xbfb8aa3b, v54
	v_exp_f32_e32 v228, v228
	s_nop 0
	v_add_f32_e32 v229, 1.0, v228
	v_div_scale_f32 v230, s[4:5], v229, v229, v54
	v_rcp_f32_e32 v231, v230
	v_div_scale_f32 v232, vcc, v54, v229, v54
	v_fma_f32 v131, -v230, v231, 1.0
	v_fmac_f32_e32 v231, v131, v231
	v_mul_f32_e32 v233, v232, v231
	v_fma_f32 v131, -v230, v233, v232
	v_fmac_f32_e32 v233, v131, v231
	v_fma_f32 v230, -v230, v233, v232
	v_div_fmas_f32 v230, v230, v231, v233
	v_div_fixup_f32 v133, v230, v229, v54
	v_mul_f32_e32 v133, v62, v133
	v_cvt_pk_bf16_f32 v133, v135, v133
	global_store_dword v[226:227], v133, off
	s_mov_b64 s[40:41], 0x1680
	v_lshl_add_u64 v[226:227], v[226:227], 0, s[40:41]
	v_mul_f32_e32 v228, 0xbfb8aa3b, v51
	v_exp_f32_e32 v228, v228
	s_nop 0
	v_add_f32_e32 v229, 1.0, v228
	v_div_scale_f32 v230, s[4:5], v229, v229, v51
	v_rcp_f32_e32 v231, v230
	v_div_scale_f32 v232, vcc, v51, v229, v51
	v_fma_f32 v131, -v230, v231, 1.0
	v_fmac_f32_e32 v231, v131, v231
	v_mul_f32_e32 v233, v232, v231
	v_fma_f32 v131, -v230, v233, v232
	v_fmac_f32_e32 v233, v131, v231
	v_fma_f32 v230, -v230, v233, v232
	v_div_fmas_f32 v230, v230, v231, v233
	v_div_fixup_f32 v135, v230, v229, v51
	v_mul_f32_e32 v135, v59, v135
	v_mul_f32_e32 v228, 0xbfb8aa3b, v55
	v_exp_f32_e32 v228, v228
	s_nop 0
	v_add_f32_e32 v229, 1.0, v228
	v_div_scale_f32 v230, s[4:5], v229, v229, v55
	v_rcp_f32_e32 v231, v230
	v_div_scale_f32 v232, vcc, v55, v229, v55
	v_fma_f32 v131, -v230, v231, 1.0
	v_fmac_f32_e32 v231, v131, v231
	v_mul_f32_e32 v233, v232, v231
	v_fma_f32 v131, -v230, v233, v232
	v_fmac_f32_e32 v233, v131, v231
	v_fma_f32 v230, -v230, v233, v232
	v_div_fmas_f32 v230, v230, v231, v233
	v_div_fixup_f32 v133, v230, v229, v55
	v_mul_f32_e32 v133, v63, v133
	v_cvt_pk_bf16_f32 v133, v135, v133
	global_store_dword v[226:227], v133, off
	s_mov_b64 s[40:41], 0x12480
	v_lshl_add_u64 v[226:227], v[226:227], 0, s[40:41]
	v_mul_f32_e32 v228, 0xbfb8aa3b, v64
	v_exp_f32_e32 v228, v228
	s_nop 0
	v_add_f32_e32 v229, 1.0, v228
	v_div_scale_f32 v230, s[4:5], v229, v229, v64
	v_rcp_f32_e32 v231, v230
	v_div_scale_f32 v232, vcc, v64, v229, v64
	v_fma_f32 v131, -v230, v231, 1.0
	v_fmac_f32_e32 v231, v131, v231
	v_mul_f32_e32 v233, v232, v231
	v_fma_f32 v131, -v230, v233, v232
	v_fmac_f32_e32 v233, v131, v231
	v_fma_f32 v230, -v230, v233, v232
	v_div_fmas_f32 v230, v230, v231, v233
	v_div_fixup_f32 v135, v230, v229, v64
	v_mul_f32_e32 v135, v72, v135
	v_mul_f32_e32 v228, 0xbfb8aa3b, v68
	v_exp_f32_e32 v228, v228
	s_nop 0
	v_add_f32_e32 v229, 1.0, v228
	v_div_scale_f32 v230, s[4:5], v229, v229, v68
	v_rcp_f32_e32 v231, v230
	v_div_scale_f32 v232, vcc, v68, v229, v68
	v_fma_f32 v131, -v230, v231, 1.0
	v_fmac_f32_e32 v231, v131, v231
	v_mul_f32_e32 v233, v232, v231
	v_fma_f32 v131, -v230, v233, v232
	v_fmac_f32_e32 v233, v131, v231
	v_fma_f32 v230, -v230, v233, v232
	v_div_fmas_f32 v230, v230, v231, v233
	v_div_fixup_f32 v133, v230, v229, v68
	v_mul_f32_e32 v133, v76, v133
	v_cvt_pk_bf16_f32 v133, v135, v133
	global_store_dword v[226:227], v133, off
	s_mov_b64 s[40:41], 0x1680
	v_lshl_add_u64 v[226:227], v[226:227], 0, s[40:41]
	v_mul_f32_e32 v228, 0xbfb8aa3b, v65
	v_exp_f32_e32 v228, v228
	s_nop 0
	v_add_f32_e32 v229, 1.0, v228
	v_div_scale_f32 v230, s[4:5], v229, v229, v65
	v_rcp_f32_e32 v231, v230
	v_div_scale_f32 v232, vcc, v65, v229, v65
	v_fma_f32 v131, -v230, v231, 1.0
	v_fmac_f32_e32 v231, v131, v231
	v_mul_f32_e32 v233, v232, v231
	v_fma_f32 v131, -v230, v233, v232
	v_fmac_f32_e32 v233, v131, v231
	v_fma_f32 v230, -v230, v233, v232
	v_div_fmas_f32 v230, v230, v231, v233
	v_div_fixup_f32 v135, v230, v229, v65
	v_mul_f32_e32 v135, v73, v135
	v_mul_f32_e32 v228, 0xbfb8aa3b, v69
	v_exp_f32_e32 v228, v228
	s_nop 0
	v_add_f32_e32 v229, 1.0, v228
	v_div_scale_f32 v230, s[4:5], v229, v229, v69
	v_rcp_f32_e32 v231, v230
	v_div_scale_f32 v232, vcc, v69, v229, v69
	v_fma_f32 v131, -v230, v231, 1.0
	v_fmac_f32_e32 v231, v131, v231
	v_mul_f32_e32 v233, v232, v231
	v_fma_f32 v131, -v230, v233, v232
	v_fmac_f32_e32 v233, v131, v231
	v_fma_f32 v230, -v230, v233, v232
	v_div_fmas_f32 v230, v230, v231, v233
	v_div_fixup_f32 v133, v230, v229, v69
	v_mul_f32_e32 v133, v77, v133
	v_cvt_pk_bf16_f32 v133, v135, v133
	global_store_dword v[226:227], v133, off
	s_mov_b64 s[40:41], 0x1680
	v_lshl_add_u64 v[226:227], v[226:227], 0, s[40:41]
	v_mul_f32_e32 v228, 0xbfb8aa3b, v66
	v_exp_f32_e32 v228, v228
	s_nop 0
	v_add_f32_e32 v229, 1.0, v228
	v_div_scale_f32 v230, s[4:5], v229, v229, v66
	v_rcp_f32_e32 v231, v230
	v_div_scale_f32 v232, vcc, v66, v229, v66
	v_fma_f32 v131, -v230, v231, 1.0
	v_fmac_f32_e32 v231, v131, v231
	v_mul_f32_e32 v233, v232, v231
	v_fma_f32 v131, -v230, v233, v232
	v_fmac_f32_e32 v233, v131, v231
	v_fma_f32 v230, -v230, v233, v232
	v_div_fmas_f32 v230, v230, v231, v233
	v_div_fixup_f32 v135, v230, v229, v66
	v_mul_f32_e32 v135, v74, v135
	v_mul_f32_e32 v228, 0xbfb8aa3b, v70
	v_exp_f32_e32 v228, v228
	s_nop 0
	v_add_f32_e32 v229, 1.0, v228
	v_div_scale_f32 v230, s[4:5], v229, v229, v70
	v_rcp_f32_e32 v231, v230
	v_div_scale_f32 v232, vcc, v70, v229, v70
	v_fma_f32 v131, -v230, v231, 1.0
	v_fmac_f32_e32 v231, v131, v231
	v_mul_f32_e32 v233, v232, v231
	v_fma_f32 v131, -v230, v233, v232
	v_fmac_f32_e32 v233, v131, v231
	v_fma_f32 v230, -v230, v233, v232
	v_div_fmas_f32 v230, v230, v231, v233
	v_div_fixup_f32 v133, v230, v229, v70
	v_mul_f32_e32 v133, v78, v133
	v_cvt_pk_bf16_f32 v133, v135, v133
	global_store_dword v[226:227], v133, off
	s_mov_b64 s[40:41], 0x1680
	v_lshl_add_u64 v[226:227], v[226:227], 0, s[40:41]
	v_mul_f32_e32 v228, 0xbfb8aa3b, v67
	v_exp_f32_e32 v228, v228
	s_nop 0
	v_add_f32_e32 v229, 1.0, v228
	v_div_scale_f32 v230, s[4:5], v229, v229, v67
	v_rcp_f32_e32 v231, v230
	v_div_scale_f32 v232, vcc, v67, v229, v67
	v_fma_f32 v131, -v230, v231, 1.0
	v_fmac_f32_e32 v231, v131, v231
	v_mul_f32_e32 v233, v232, v231
	v_fma_f32 v131, -v230, v233, v232
	v_fmac_f32_e32 v233, v131, v231
	v_fma_f32 v230, -v230, v233, v232
	v_div_fmas_f32 v230, v230, v231, v233
	v_div_fixup_f32 v135, v230, v229, v67
	v_mul_f32_e32 v135, v75, v135
	v_mul_f32_e32 v228, 0xbfb8aa3b, v71
	v_exp_f32_e32 v228, v228
	s_nop 0
	v_add_f32_e32 v229, 1.0, v228
	v_div_scale_f32 v230, s[4:5], v229, v229, v71
	v_rcp_f32_e32 v231, v230
	v_div_scale_f32 v232, vcc, v71, v229, v71
	v_fma_f32 v131, -v230, v231, 1.0
	v_fmac_f32_e32 v231, v131, v231
	v_mul_f32_e32 v233, v232, v231
	v_fma_f32 v131, -v230, v233, v232
	v_fmac_f32_e32 v233, v131, v231
	v_fma_f32 v230, -v230, v233, v232
	v_div_fmas_f32 v230, v230, v231, v233
	v_div_fixup_f32 v133, v230, v229, v71
	v_mul_f32_e32 v133, v79, v133
	v_cvt_pk_bf16_f32 v133, v135, v133
	global_store_dword v[226:227], v133, off
	s_mov_b64 s[40:41], 0x12480
	v_lshl_add_u64 v[226:227], v[226:227], 0, s[40:41]
	v_mul_f32_e32 v228, 0xbfb8aa3b, v80
	v_exp_f32_e32 v228, v228
	s_nop 0
	v_add_f32_e32 v229, 1.0, v228
	v_div_scale_f32 v230, s[4:5], v229, v229, v80
	v_rcp_f32_e32 v231, v230
	v_div_scale_f32 v232, vcc, v80, v229, v80
	v_fma_f32 v131, -v230, v231, 1.0
	v_fmac_f32_e32 v231, v131, v231
	v_mul_f32_e32 v233, v232, v231
	v_fma_f32 v131, -v230, v233, v232
	v_fmac_f32_e32 v233, v131, v231
	v_fma_f32 v230, -v230, v233, v232
	v_div_fmas_f32 v230, v230, v231, v233
	v_div_fixup_f32 v135, v230, v229, v80
	v_mul_f32_e32 v135, v88, v135
	v_mul_f32_e32 v228, 0xbfb8aa3b, v84
	v_exp_f32_e32 v228, v228
	s_nop 0
	v_add_f32_e32 v229, 1.0, v228
	v_div_scale_f32 v230, s[4:5], v229, v229, v84
	v_rcp_f32_e32 v231, v230
	v_div_scale_f32 v232, vcc, v84, v229, v84
	v_fma_f32 v131, -v230, v231, 1.0
	v_fmac_f32_e32 v231, v131, v231
	v_mul_f32_e32 v233, v232, v231
	v_fma_f32 v131, -v230, v233, v232
	v_fmac_f32_e32 v233, v131, v231
	v_fma_f32 v230, -v230, v233, v232
	v_div_fmas_f32 v230, v230, v231, v233
	v_div_fixup_f32 v133, v230, v229, v84
	v_mul_f32_e32 v133, v92, v133
	v_cvt_pk_bf16_f32 v133, v135, v133
	global_store_dword v[226:227], v133, off
	s_mov_b64 s[40:41], 0x1680
	v_lshl_add_u64 v[226:227], v[226:227], 0, s[40:41]
	v_mul_f32_e32 v228, 0xbfb8aa3b, v81
	v_exp_f32_e32 v228, v228
	s_nop 0
	v_add_f32_e32 v229, 1.0, v228
	v_div_scale_f32 v230, s[4:5], v229, v229, v81
	v_rcp_f32_e32 v231, v230
	v_div_scale_f32 v232, vcc, v81, v229, v81
	v_fma_f32 v131, -v230, v231, 1.0
	v_fmac_f32_e32 v231, v131, v231
	v_mul_f32_e32 v233, v232, v231
	v_fma_f32 v131, -v230, v233, v232
	v_fmac_f32_e32 v233, v131, v231
	v_fma_f32 v230, -v230, v233, v232
	v_div_fmas_f32 v230, v230, v231, v233
	v_div_fixup_f32 v135, v230, v229, v81
	v_mul_f32_e32 v135, v89, v135
	v_mul_f32_e32 v228, 0xbfb8aa3b, v85
	v_exp_f32_e32 v228, v228
	s_nop 0
	v_add_f32_e32 v229, 1.0, v228
	v_div_scale_f32 v230, s[4:5], v229, v229, v85
	v_rcp_f32_e32 v231, v230
	v_div_scale_f32 v232, vcc, v85, v229, v85
	v_fma_f32 v131, -v230, v231, 1.0
	v_fmac_f32_e32 v231, v131, v231
	v_mul_f32_e32 v233, v232, v231
	v_fma_f32 v131, -v230, v233, v232
	v_fmac_f32_e32 v233, v131, v231
	v_fma_f32 v230, -v230, v233, v232
	v_div_fmas_f32 v230, v230, v231, v233
	v_div_fixup_f32 v133, v230, v229, v85
	v_mul_f32_e32 v133, v93, v133
	v_cvt_pk_bf16_f32 v133, v135, v133
	global_store_dword v[226:227], v133, off
	s_mov_b64 s[40:41], 0x1680
	v_lshl_add_u64 v[226:227], v[226:227], 0, s[40:41]
	v_mul_f32_e32 v228, 0xbfb8aa3b, v82
	v_exp_f32_e32 v228, v228
	s_nop 0
	v_add_f32_e32 v229, 1.0, v228
	v_div_scale_f32 v230, s[4:5], v229, v229, v82
	v_rcp_f32_e32 v231, v230
	v_div_scale_f32 v232, vcc, v82, v229, v82
	v_fma_f32 v131, -v230, v231, 1.0
	v_fmac_f32_e32 v231, v131, v231
	v_mul_f32_e32 v233, v232, v231
	v_fma_f32 v131, -v230, v233, v232
	v_fmac_f32_e32 v233, v131, v231
	v_fma_f32 v230, -v230, v233, v232
	v_div_fmas_f32 v230, v230, v231, v233
	v_div_fixup_f32 v135, v230, v229, v82
	v_mul_f32_e32 v135, v90, v135
	v_mul_f32_e32 v228, 0xbfb8aa3b, v86
	v_exp_f32_e32 v228, v228
	s_nop 0
	v_add_f32_e32 v229, 1.0, v228
	v_div_scale_f32 v230, s[4:5], v229, v229, v86
	v_rcp_f32_e32 v231, v230
	v_div_scale_f32 v232, vcc, v86, v229, v86
	v_fma_f32 v131, -v230, v231, 1.0
	v_fmac_f32_e32 v231, v131, v231
	v_mul_f32_e32 v233, v232, v231
	v_fma_f32 v131, -v230, v233, v232
	v_fmac_f32_e32 v233, v131, v231
	v_fma_f32 v230, -v230, v233, v232
	v_div_fmas_f32 v230, v230, v231, v233
	v_div_fixup_f32 v133, v230, v229, v86
	v_mul_f32_e32 v133, v94, v133
	v_cvt_pk_bf16_f32 v133, v135, v133
	global_store_dword v[226:227], v133, off
	s_mov_b64 s[40:41], 0x1680
	v_lshl_add_u64 v[226:227], v[226:227], 0, s[40:41]
	v_mul_f32_e32 v228, 0xbfb8aa3b, v83
	v_exp_f32_e32 v228, v228
	s_nop 0
	v_add_f32_e32 v229, 1.0, v228
	v_div_scale_f32 v230, s[4:5], v229, v229, v83
	v_rcp_f32_e32 v231, v230
	v_div_scale_f32 v232, vcc, v83, v229, v83
	v_fma_f32 v131, -v230, v231, 1.0
	v_fmac_f32_e32 v231, v131, v231
	v_mul_f32_e32 v233, v232, v231
	v_fma_f32 v131, -v230, v233, v232
	v_fmac_f32_e32 v233, v131, v231
	v_fma_f32 v230, -v230, v233, v232
	v_div_fmas_f32 v230, v230, v231, v233
	v_div_fixup_f32 v135, v230, v229, v83
	v_mul_f32_e32 v135, v91, v135
	v_mul_f32_e32 v228, 0xbfb8aa3b, v87
	v_exp_f32_e32 v228, v228
	s_nop 0
	v_add_f32_e32 v229, 1.0, v228
	v_div_scale_f32 v230, s[4:5], v229, v229, v87
	v_rcp_f32_e32 v231, v230
	v_div_scale_f32 v232, vcc, v87, v229, v87
	v_fma_f32 v131, -v230, v231, 1.0
	v_fmac_f32_e32 v231, v131, v231
	v_mul_f32_e32 v233, v232, v231
	v_fma_f32 v131, -v230, v233, v232
	v_fmac_f32_e32 v233, v131, v231
	v_fma_f32 v230, -v230, v233, v232
	v_div_fmas_f32 v230, v230, v231, v233
	v_div_fixup_f32 v133, v230, v229, v87
	v_mul_f32_e32 v133, v95, v133
	v_cvt_pk_bf16_f32 v133, v135, v133
	global_store_dword v[226:227], v133, off
	s_mov_b64 s[40:41], 0x12480
	v_lshl_add_u64 v[226:227], v[226:227], 0, s[40:41]
	v_mul_f32_e32 v228, 0xbfb8aa3b, v96
	v_exp_f32_e32 v228, v228
	s_nop 0
	v_add_f32_e32 v229, 1.0, v228
	v_div_scale_f32 v230, s[4:5], v229, v229, v96
	v_rcp_f32_e32 v231, v230
	v_div_scale_f32 v232, vcc, v96, v229, v96
	v_fma_f32 v131, -v230, v231, 1.0
	v_fmac_f32_e32 v231, v131, v231
	v_mul_f32_e32 v233, v232, v231
	v_fma_f32 v131, -v230, v233, v232
	v_fmac_f32_e32 v233, v131, v231
	v_fma_f32 v230, -v230, v233, v232
	v_div_fmas_f32 v230, v230, v231, v233
	v_div_fixup_f32 v135, v230, v229, v96
	v_mul_f32_e32 v135, v104, v135
	v_mul_f32_e32 v228, 0xbfb8aa3b, v100
	v_exp_f32_e32 v228, v228
	s_nop 0
	v_add_f32_e32 v229, 1.0, v228
	v_div_scale_f32 v230, s[4:5], v229, v229, v100
	v_rcp_f32_e32 v231, v230
	v_div_scale_f32 v232, vcc, v100, v229, v100
	v_fma_f32 v131, -v230, v231, 1.0
	v_fmac_f32_e32 v231, v131, v231
	v_mul_f32_e32 v233, v232, v231
	v_fma_f32 v131, -v230, v233, v232
	v_fmac_f32_e32 v233, v131, v231
	v_fma_f32 v230, -v230, v233, v232
	v_div_fmas_f32 v230, v230, v231, v233
	v_div_fixup_f32 v133, v230, v229, v100
	v_mul_f32_e32 v133, v108, v133
	v_cvt_pk_bf16_f32 v133, v135, v133
	global_store_dword v[226:227], v133, off
	s_mov_b64 s[40:41], 0x1680
	v_lshl_add_u64 v[226:227], v[226:227], 0, s[40:41]
	v_mul_f32_e32 v228, 0xbfb8aa3b, v97
	v_exp_f32_e32 v228, v228
	s_nop 0
	v_add_f32_e32 v229, 1.0, v228
	v_div_scale_f32 v230, s[4:5], v229, v229, v97
	v_rcp_f32_e32 v231, v230
	v_div_scale_f32 v232, vcc, v97, v229, v97
	v_fma_f32 v131, -v230, v231, 1.0
	v_fmac_f32_e32 v231, v131, v231
	v_mul_f32_e32 v233, v232, v231
	v_fma_f32 v131, -v230, v233, v232
	v_fmac_f32_e32 v233, v131, v231
	v_fma_f32 v230, -v230, v233, v232
	v_div_fmas_f32 v230, v230, v231, v233
	v_div_fixup_f32 v135, v230, v229, v97
	v_mul_f32_e32 v135, v105, v135
	v_mul_f32_e32 v228, 0xbfb8aa3b, v101
	v_exp_f32_e32 v228, v228
	s_nop 0
	v_add_f32_e32 v229, 1.0, v228
	v_div_scale_f32 v230, s[4:5], v229, v229, v101
	v_rcp_f32_e32 v231, v230
	v_div_scale_f32 v232, vcc, v101, v229, v101
	v_fma_f32 v131, -v230, v231, 1.0
	v_fmac_f32_e32 v231, v131, v231
	v_mul_f32_e32 v233, v232, v231
	v_fma_f32 v131, -v230, v233, v232
	v_fmac_f32_e32 v233, v131, v231
	v_fma_f32 v230, -v230, v233, v232
	v_div_fmas_f32 v230, v230, v231, v233
	v_div_fixup_f32 v133, v230, v229, v101
	v_mul_f32_e32 v133, v109, v133
	v_cvt_pk_bf16_f32 v133, v135, v133
	global_store_dword v[226:227], v133, off
	s_mov_b64 s[40:41], 0x1680
	v_lshl_add_u64 v[226:227], v[226:227], 0, s[40:41]
	v_mul_f32_e32 v228, 0xbfb8aa3b, v98
	v_exp_f32_e32 v228, v228
	s_nop 0
	v_add_f32_e32 v229, 1.0, v228
	v_div_scale_f32 v230, s[4:5], v229, v229, v98
	v_rcp_f32_e32 v231, v230
	v_div_scale_f32 v232, vcc, v98, v229, v98
	v_fma_f32 v131, -v230, v231, 1.0
	v_fmac_f32_e32 v231, v131, v231
	v_mul_f32_e32 v233, v232, v231
	v_fma_f32 v131, -v230, v233, v232
	v_fmac_f32_e32 v233, v131, v231
	v_fma_f32 v230, -v230, v233, v232
	v_div_fmas_f32 v230, v230, v231, v233
	v_div_fixup_f32 v135, v230, v229, v98
	v_mul_f32_e32 v135, v106, v135
	v_mul_f32_e32 v228, 0xbfb8aa3b, v102
	v_exp_f32_e32 v228, v228
	s_nop 0
	v_add_f32_e32 v229, 1.0, v228
	v_div_scale_f32 v230, s[4:5], v229, v229, v102
	v_rcp_f32_e32 v231, v230
	v_div_scale_f32 v232, vcc, v102, v229, v102
	v_fma_f32 v131, -v230, v231, 1.0
	v_fmac_f32_e32 v231, v131, v231
	v_mul_f32_e32 v233, v232, v231
	v_fma_f32 v131, -v230, v233, v232
	v_fmac_f32_e32 v233, v131, v231
	v_fma_f32 v230, -v230, v233, v232
	v_div_fmas_f32 v230, v230, v231, v233
	v_div_fixup_f32 v133, v230, v229, v102
	v_mul_f32_e32 v133, v110, v133
	v_cvt_pk_bf16_f32 v133, v135, v133
	global_store_dword v[226:227], v133, off
	s_mov_b64 s[40:41], 0x1680
	v_lshl_add_u64 v[226:227], v[226:227], 0, s[40:41]
	v_mul_f32_e32 v228, 0xbfb8aa3b, v99
	v_exp_f32_e32 v228, v228
	s_nop 0
	v_add_f32_e32 v229, 1.0, v228
	v_div_scale_f32 v230, s[4:5], v229, v229, v99
	v_rcp_f32_e32 v231, v230
	v_div_scale_f32 v232, vcc, v99, v229, v99
	v_fma_f32 v131, -v230, v231, 1.0
	v_fmac_f32_e32 v231, v131, v231
	v_mul_f32_e32 v233, v232, v231
	v_fma_f32 v131, -v230, v233, v232
	v_fmac_f32_e32 v233, v131, v231
	v_fma_f32 v230, -v230, v233, v232
	v_div_fmas_f32 v230, v230, v231, v233
	v_div_fixup_f32 v135, v230, v229, v99
	v_mul_f32_e32 v135, v107, v135
	v_mul_f32_e32 v228, 0xbfb8aa3b, v103
	v_exp_f32_e32 v228, v228
	s_nop 0
	v_add_f32_e32 v229, 1.0, v228
	v_div_scale_f32 v230, s[4:5], v229, v229, v103
	v_rcp_f32_e32 v231, v230
	v_div_scale_f32 v232, vcc, v103, v229, v103
	v_fma_f32 v131, -v230, v231, 1.0
	v_fmac_f32_e32 v231, v131, v231
	v_mul_f32_e32 v233, v232, v231
	v_fma_f32 v131, -v230, v233, v232
	v_fmac_f32_e32 v233, v131, v231
	v_fma_f32 v230, -v230, v233, v232
	v_div_fmas_f32 v230, v230, v231, v233
	v_div_fixup_f32 v133, v230, v229, v103
	v_mul_f32_e32 v133, v111, v133
	v_cvt_pk_bf16_f32 v133, v135, v133
	global_store_dword v[226:227], v133, off
	s_mov_b64 s[40:41], 0x12480
	v_lshl_add_u64 v[226:227], v[226:227], 0, s[40:41]
	v_mul_f32_e32 v228, 0xbfb8aa3b, v112
	v_exp_f32_e32 v228, v228
	s_nop 0
	v_add_f32_e32 v229, 1.0, v228
	v_div_scale_f32 v230, s[4:5], v229, v229, v112
	v_rcp_f32_e32 v231, v230
	v_div_scale_f32 v232, vcc, v112, v229, v112
	v_fma_f32 v131, -v230, v231, 1.0
	v_fmac_f32_e32 v231, v131, v231
	v_mul_f32_e32 v233, v232, v231
	v_fma_f32 v131, -v230, v233, v232
	v_fmac_f32_e32 v233, v131, v231
	v_fma_f32 v230, -v230, v233, v232
	v_div_fmas_f32 v230, v230, v231, v233
	v_div_fixup_f32 v135, v230, v229, v112
	v_mul_f32_e32 v135, v120, v135
	v_mul_f32_e32 v228, 0xbfb8aa3b, v116
	v_exp_f32_e32 v228, v228
	s_nop 0
	v_add_f32_e32 v229, 1.0, v228
	v_div_scale_f32 v230, s[4:5], v229, v229, v116
	v_rcp_f32_e32 v231, v230
	v_div_scale_f32 v232, vcc, v116, v229, v116
	v_fma_f32 v131, -v230, v231, 1.0
	v_fmac_f32_e32 v231, v131, v231
	v_mul_f32_e32 v233, v232, v231
	v_fma_f32 v131, -v230, v233, v232
	v_fmac_f32_e32 v233, v131, v231
	v_fma_f32 v230, -v230, v233, v232
	v_div_fmas_f32 v230, v230, v231, v233
	v_div_fixup_f32 v133, v230, v229, v116
	v_mul_f32_e32 v133, v124, v133
	v_cvt_pk_bf16_f32 v133, v135, v133
	global_store_dword v[226:227], v133, off
	s_mov_b64 s[40:41], 0x1680
	v_lshl_add_u64 v[226:227], v[226:227], 0, s[40:41]
	v_mul_f32_e32 v228, 0xbfb8aa3b, v113
	v_exp_f32_e32 v228, v228
	s_nop 0
	v_add_f32_e32 v229, 1.0, v228
	v_div_scale_f32 v230, s[4:5], v229, v229, v113
	v_rcp_f32_e32 v231, v230
	v_div_scale_f32 v232, vcc, v113, v229, v113
	v_fma_f32 v131, -v230, v231, 1.0
	v_fmac_f32_e32 v231, v131, v231
	v_mul_f32_e32 v233, v232, v231
	v_fma_f32 v131, -v230, v233, v232
	v_fmac_f32_e32 v233, v131, v231
	v_fma_f32 v230, -v230, v233, v232
	v_div_fmas_f32 v230, v230, v231, v233
	v_div_fixup_f32 v135, v230, v229, v113
	v_mul_f32_e32 v135, v121, v135
	v_mul_f32_e32 v228, 0xbfb8aa3b, v117
	v_exp_f32_e32 v228, v228
	s_nop 0
	v_add_f32_e32 v229, 1.0, v228
	v_div_scale_f32 v230, s[4:5], v229, v229, v117
	v_rcp_f32_e32 v231, v230
	v_div_scale_f32 v232, vcc, v117, v229, v117
	v_fma_f32 v131, -v230, v231, 1.0
	v_fmac_f32_e32 v231, v131, v231
	v_mul_f32_e32 v233, v232, v231
	v_fma_f32 v131, -v230, v233, v232
	v_fmac_f32_e32 v233, v131, v231
	v_fma_f32 v230, -v230, v233, v232
	v_div_fmas_f32 v230, v230, v231, v233
	v_div_fixup_f32 v133, v230, v229, v117
	v_mul_f32_e32 v133, v125, v133
	v_cvt_pk_bf16_f32 v133, v135, v133
	global_store_dword v[226:227], v133, off
	s_mov_b64 s[40:41], 0x1680
	v_lshl_add_u64 v[226:227], v[226:227], 0, s[40:41]
	v_mul_f32_e32 v228, 0xbfb8aa3b, v114
	v_exp_f32_e32 v228, v228
	s_nop 0
	v_add_f32_e32 v229, 1.0, v228
	v_div_scale_f32 v230, s[4:5], v229, v229, v114
	v_rcp_f32_e32 v231, v230
	v_div_scale_f32 v232, vcc, v114, v229, v114
	v_fma_f32 v131, -v230, v231, 1.0
	v_fmac_f32_e32 v231, v131, v231
	v_mul_f32_e32 v233, v232, v231
	v_fma_f32 v131, -v230, v233, v232
	v_fmac_f32_e32 v233, v131, v231
	v_fma_f32 v230, -v230, v233, v232
	v_div_fmas_f32 v230, v230, v231, v233
	v_div_fixup_f32 v135, v230, v229, v114
	v_mul_f32_e32 v135, v122, v135
	v_mul_f32_e32 v228, 0xbfb8aa3b, v118
	v_exp_f32_e32 v228, v228
	s_nop 0
	v_add_f32_e32 v229, 1.0, v228
	v_div_scale_f32 v230, s[4:5], v229, v229, v118
	v_rcp_f32_e32 v231, v230
	v_div_scale_f32 v232, vcc, v118, v229, v118
	v_fma_f32 v131, -v230, v231, 1.0
	v_fmac_f32_e32 v231, v131, v231
	v_mul_f32_e32 v233, v232, v231
	v_fma_f32 v131, -v230, v233, v232
	v_fmac_f32_e32 v233, v131, v231
	v_fma_f32 v230, -v230, v233, v232
	v_div_fmas_f32 v230, v230, v231, v233
	v_div_fixup_f32 v133, v230, v229, v118
	v_mul_f32_e32 v133, v126, v133
	v_cvt_pk_bf16_f32 v133, v135, v133
	global_store_dword v[226:227], v133, off
	s_mov_b64 s[40:41], 0x1680
	v_lshl_add_u64 v[226:227], v[226:227], 0, s[40:41]
	v_mul_f32_e32 v228, 0xbfb8aa3b, v115
	v_exp_f32_e32 v228, v228
	s_nop 0
	v_add_f32_e32 v229, 1.0, v228
	v_div_scale_f32 v230, s[4:5], v229, v229, v115
	v_rcp_f32_e32 v231, v230
	v_div_scale_f32 v232, vcc, v115, v229, v115
	v_fma_f32 v131, -v230, v231, 1.0
	v_fmac_f32_e32 v231, v131, v231
	v_mul_f32_e32 v233, v232, v231
	v_fma_f32 v131, -v230, v233, v232
	v_fmac_f32_e32 v233, v131, v231
	v_fma_f32 v230, -v230, v233, v232
	v_div_fmas_f32 v230, v230, v231, v233
	v_div_fixup_f32 v135, v230, v229, v115
	v_mul_f32_e32 v135, v123, v135
	v_mul_f32_e32 v228, 0xbfb8aa3b, v119
	v_exp_f32_e32 v228, v228
	s_nop 0
	v_add_f32_e32 v229, 1.0, v228
	v_div_scale_f32 v230, s[4:5], v229, v229, v119
	v_rcp_f32_e32 v231, v230
	v_div_scale_f32 v232, vcc, v119, v229, v119
	v_fma_f32 v131, -v230, v231, 1.0
	v_fmac_f32_e32 v231, v131, v231
	v_mul_f32_e32 v233, v232, v231
	v_fma_f32 v131, -v230, v233, v232
	v_fmac_f32_e32 v233, v131, v231
	v_fma_f32 v230, -v230, v233, v232
	v_div_fmas_f32 v230, v230, v231, v233
	v_div_fixup_f32 v133, v230, v229, v119
	v_mul_f32_e32 v133, v127, v133
	v_cvt_pk_bf16_f32 v133, v135, v133
	global_store_dword v[226:227], v133, off
	v_readlane_b32 s40, v239, 0
	s_cmp_ge_u32 s54, s40
	s_cbranch_scc1 .Lfi_main_done
	s_lshr_b32 s55, s54, 4
	s_mul_hi_u32 s55, s55, 0x55555556
	s_mul_i32 s53, s55, 48
	s_sub_u32 s53, s54, s53
	v_readlane_b32 s4, v235, 34
	v_readlane_b32 s5, v235, 35
	s_mul_i32 s50, s53, 0x168000
	s_lshl_b32 s55, s55, 7
	s_add_u32 s50, s50, s55
	s_add_u32 s50, s50, 0xfae6000
	s_add_u32 s50, s50, s4
	s_addc_u32 s51, s5, 0
	s_branch .Lfi_tile
.Lfi_main_done:
	v_readlane_b32 s40, v239, 0
	s_cmp_eq_u32 s40, 2112
	s_cbranch_scc1 .Lfi_done
	v_readlane_b32 s55, v237, 0
	s_cmp_ge_u32 s55, 128
	s_cbranch_scc1 .Lfi_done
	s_and_b32 s56, s55, 1
	s_lshr_b32 s54, s55, 1
	s_add_u32 s54, s54, 2048
	v_and_b32_e32 v225, 63, v170
	v_lshrrev_b32_e32 v226, 6, v170
	v_and_b32_e32 v229, 15, v225
	v_lshrrev_b32_e32 v230, 4, v225
	v_lshlrev_b32_e32 v231, 10, v226
	v_lshrrev_b32_e32 v232, 3, v170
	v_readfirstlane_b32 s52, v231
	v_and_b32_e32 v233, 7, v170
	v_bfe_u32 v224, v232, 1, 3
	v_xor_b32_e32 v233, v233, v224
	v_lshlrev_b32_e32 v233, 4, v233
	s_movk_i32 s4, 0x880
	v_mad_u32_u24 v224, v232, s4, v233
	v_and_b32_e32 v233, 15, v232
	v_lshlrev_b32_e32 v233, 1, v233
	v_lshrrev_b32_e32 v168, 4, v232
	v_add_u32_e32 v233, v233, v168
	v_and_b32_e32 v168, 7, v170
	v_bfe_u32 v169, v232, 1, 3
	v_xor_b32_e32 v168, v168, v169
	v_lshlrev_b32_e32 v168, 4, v168
	v_mad_u32_u24 v168, v233, s4, v168
	v_bfe_u32 v233, v229, 1, 3
	v_xor_b32_e32 v231, v230, v233
	v_or_b32_e32 v232, 4, v230
	v_xor_b32_e32 v232, v232, v233
	v_lshlrev_b32_e32 v231, 4, v231
	v_lshlrev_b32_e32 v232, 4, v232
	v_lshl_add_u32 v233, v226, 6, v229
	v_lshlrev_b32_e32 v233, 7, v233
	v_add_u32_e32 v220, v233, v231
	v_add_u32_e32 v221, v233, v232
	v_mov_b32_e32 v233, v229
	v_lshlrev_b32_e32 v233, 7, v233
	v_add_u32_e32 v233, 0x8000, v233
	v_add_u32_e32 v222, v233, v231
	v_add_u32_e32 v223, v233, v232
	v_lshlrev_b32_e32 v233, 6, v226
	v_lshl_add_u32 v233, v230, 2, v233
	v_lshlrev_b32_e32 v227, 2, v229
	s_movk_i32 s4, 0x1680
	v_mad_u32_u24 v225, v233, s4, v227
	s_lshr_b32 s55, s54, 4
	s_mul_hi_u32 s55, s55, 0x55555556
	s_mul_i32 s53, s55, 48
	s_sub_u32 s53, s54, s53
	v_readlane_b32 s4, v235, 34
	v_readlane_b32 s5, v235, 35
	s_mul_i32 s44, s53, 0x88000
	s_add_u32 s44, s44, 0xe166000
	s_add_u32 s44, s44, s4
	s_addc_u32 s45, s5, 0
	s_mul_i32 s46, s55, 0x44000
	s_mul_i32 s57, s56, 0x22000
	s_add_u32 s46, s46, s57
	s_add_u32 s46, s46, s36
	s_addc_u32 s47, s37, 0
	s_lshr_b32 s55, s54, 4
	s_mul_hi_u32 s55, s55, 0x55555556
	s_mul_i32 s53, s55, 48
	s_sub_u32 s53, s54, s53
	v_readlane_b32 s4, v235, 34
	v_readlane_b32 s5, v235, 35
	s_mul_i32 s50, s53, 0x168000
	s_lshl_b32 s55, s55, 7
	s_add_u32 s50, s50, s55
	s_add_u32 s50, s50, 0xfae6000
	s_lshl_b32 s57, s56, 6
	s_add_u32 s50, s50, s57
	s_add_u32 s50, s50, s4
	s_addc_u32 s51, s5, 0
	s_add_u32 m0, s52, 0x0
	s_add_u32 s4, s44, 0x0
	s_addc_u32 s5, s45, 0
	global_load_lds_dwordx4 v224, s[4:5]
	s_add_u32 m0, s52, 0x1000
	s_add_u32 s4, s44, 0x11000
	s_addc_u32 s5, s45, 0
	global_load_lds_dwordx4 v224, s[4:5]
	s_add_u32 m0, s52, 0x2000
	s_add_u32 s4, s44, 0x22000
	s_addc_u32 s5, s45, 0
	global_load_lds_dwordx4 v224, s[4:5]
	s_add_u32 m0, s52, 0x3000
	s_add_u32 s4, s44, 0x33000
	s_addc_u32 s5, s45, 0
	global_load_lds_dwordx4 v224, s[4:5]
	s_add_u32 m0, s52, 0x4000
	s_add_u32 s4, s44, 0x44000
	s_addc_u32 s5, s45, 0
	global_load_lds_dwordx4 v224, s[4:5]
	s_add_u32 m0, s52, 0x5000
	s_add_u32 s4, s44, 0x55000
	s_addc_u32 s5, s45, 0
	global_load_lds_dwordx4 v224, s[4:5]
	s_add_u32 m0, s52, 0x6000
	s_add_u32 s4, s44, 0x66000
	s_addc_u32 s5, s45, 0
	global_load_lds_dwordx4 v224, s[4:5]
	s_add_u32 m0, s52, 0x7000
	s_add_u32 s4, s44, 0x77000
	s_addc_u32 s5, s45, 0
	global_load_lds_dwordx4 v224, s[4:5]
	s_add_u32 m0, s52, 0x8000
	s_add_u32 s4, s46, 0x0
	s_addc_u32 s5, s47, 0
	global_load_lds_dwordx4 v168, s[4:5]
	s_add_u32 m0, s52, 0x9000
	s_add_u32 s4, s46, 0x11000
	s_addc_u32 s5, s47, 0
	global_load_lds_dwordx4 v168, s[4:5]
	s_add_u32 s44, s44, 0x80
	s_addc_u32 s45, s45, 0
	s_add_u32 s46, s46, 0x80
	s_addc_u32 s47, s47, 0
	v_mov_b32_e32 v0, 0
	v_mov_b32_e32 v1, 0
	v_mov_b32_e32 v2, 0
	v_mov_b32_e32 v3, 0
	v_mov_b32_e32 v4, 0
	v_mov_b32_e32 v5, 0
	v_mov_b32_e32 v6, 0
	v_mov_b32_e32 v7, 0
	v_mov_b32_e32 v8, 0
	v_mov_b32_e32 v9, 0
	v_mov_b32_e32 v10, 0
	v_mov_b32_e32 v11, 0
	v_mov_b32_e32 v12, 0
	v_mov_b32_e32 v13, 0
	v_mov_b32_e32 v14, 0
	v_mov_b32_e32 v15, 0
	v_mov_b32_e32 v16, 0
	v_mov_b32_e32 v17, 0
	v_mov_b32_e32 v18, 0
	v_mov_b32_e32 v19, 0
	v_mov_b32_e32 v20, 0
	v_mov_b32_e32 v21, 0
	v_mov_b32_e32 v22, 0
	v_mov_b32_e32 v23, 0
	v_mov_b32_e32 v24, 0
	v_mov_b32_e32 v25, 0
	v_mov_b32_e32 v26, 0
	v_mov_b32_e32 v27, 0
	v_mov_b32_e32 v28, 0
	v_mov_b32_e32 v29, 0
	v_mov_b32_e32 v30, 0
	v_mov_b32_e32 v31, 0
	v_mov_b32_e32 v32, 0
	v_mov_b32_e32 v33, 0
	v_mov_b32_e32 v34, 0
	v_mov_b32_e32 v35, 0
	v_mov_b32_e32 v36, 0
	v_mov_b32_e32 v37, 0
	v_mov_b32_e32 v38, 0
	v_mov_b32_e32 v39, 0
	v_mov_b32_e32 v40, 0
	v_mov_b32_e32 v41, 0
	v_mov_b32_e32 v42, 0
	v_mov_b32_e32 v43, 0
	v_mov_b32_e32 v44, 0
	v_mov_b32_e32 v45, 0
	v_mov_b32_e32 v46, 0
	v_mov_b32_e32 v47, 0
	v_mov_b32_e32 v48, 0
	v_mov_b32_e32 v49, 0
	v_mov_b32_e32 v50, 0
	v_mov_b32_e32 v51, 0
	v_mov_b32_e32 v52, 0
	v_mov_b32_e32 v53, 0
	v_mov_b32_e32 v54, 0
	v_mov_b32_e32 v55, 0
	v_mov_b32_e32 v56, 0
	v_mov_b32_e32 v57, 0
	v_mov_b32_e32 v58, 0
	v_mov_b32_e32 v59, 0
	v_mov_b32_e32 v60, 0
	v_mov_b32_e32 v61, 0
	v_mov_b32_e32 v62, 0
	v_mov_b32_e32 v63, 0
	s_mov_b32 s53, 0
.Lfh_k:
	s_waitcnt vmcnt(0)
	s_barrier
	ds_read_b128 v[204:207], v222
	ds_read_b128 v[208:211], v222 offset:2048
	ds_read_b128 v[212:215], v222 offset:4096
	ds_read_b128 v[216:219], v222 offset:6144
	ds_read_b128 a[0:3], v223
	ds_read_b128 a[4:7], v223 offset:2048
	ds_read_b128 a[8:11], v223 offset:4096
	ds_read_b128 a[12:15], v223 offset:6144
	ds_read_b128 v[136:139], v220
	ds_read_b128 v[140:143], v220 offset:2048
	ds_read_b128 v[144:147], v220 offset:4096
	ds_read_b128 v[148:151], v220 offset:6144
	s_waitcnt lgkmcnt(3)
	v_mfma_f32_16x16x32_bf16 v[0:3], v[136:139], v[204:207], v[0:3]
	v_mfma_f32_16x16x32_bf16 v[4:7], v[136:139], v[208:211], v[4:7]
	v_mfma_f32_16x16x32_bf16 v[8:11], v[136:139], v[212:215], v[8:11]
	v_mfma_f32_16x16x32_bf16 v[12:15], v[136:139], v[216:219], v[12:15]
	ds_read_b128 v[136:139], v221
	s_waitcnt lgkmcnt(3)
	v_mfma_f32_16x16x32_bf16 v[16:19], v[140:143], v[204:207], v[16:19]
	v_mfma_f32_16x16x32_bf16 v[20:23], v[140:143], v[208:211], v[20:23]
	v_mfma_f32_16x16x32_bf16 v[24:27], v[140:143], v[212:215], v[24:27]
	v_mfma_f32_16x16x32_bf16 v[28:31], v[140:143], v[216:219], v[28:31]
	ds_read_b128 v[140:143], v221 offset:2048
	s_waitcnt lgkmcnt(3)
	v_mfma_f32_16x16x32_bf16 v[32:35], v[144:147], v[204:207], v[32:35]
	v_mfma_f32_16x16x32_bf16 v[36:39], v[144:147], v[208:211], v[36:39]
	v_mfma_f32_16x16x32_bf16 v[40:43], v[144:147], v[212:215], v[40:43]
	v_mfma_f32_16x16x32_bf16 v[44:47], v[144:147], v[216:219], v[44:47]
	ds_read_b128 v[144:147], v221 offset:4096
	s_waitcnt lgkmcnt(3)
	v_mfma_f32_16x16x32_bf16 v[48:51], v[148:151], v[204:207], v[48:51]
	v_mfma_f32_16x16x32_bf16 v[52:55], v[148:151], v[208:211], v[52:55]
	v_mfma_f32_16x16x32_bf16 v[56:59], v[148:151], v[212:215], v[56:59]
	v_mfma_f32_16x16x32_bf16 v[60:63], v[148:151], v[216:219], v[60:63]
	ds_read_b128 v[148:151], v221 offset:6144
	s_waitcnt lgkmcnt(0)
	s_barrier
	s_cmp_eq_u32 s53, 15
	s_cbranch_scc1 .Lfh_last
	s_add_u32 m0, s52, 0x0
	s_add_u32 s4, s44, 0x0
	s_addc_u32 s5, s45, 0
	global_load_lds_dwordx4 v224, s[4:5]
	s_add_u32 m0, s52, 0x1000
	s_add_u32 s4, s44, 0x11000
	s_addc_u32 s5, s45, 0
	global_load_lds_dwordx4 v224, s[4:5]
	s_add_u32 m0, s52, 0x2000
	s_add_u32 s4, s44, 0x22000
	s_addc_u32 s5, s45, 0
	global_load_lds_dwordx4 v224, s[4:5]
	s_add_u32 m0, s52, 0x3000
	s_add_u32 s4, s44, 0x33000
	s_addc_u32 s5, s45, 0
	global_load_lds_dwordx4 v224, s[4:5]
	s_add_u32 m0, s52, 0x4000
	s_add_u32 s4, s44, 0x44000
	s_addc_u32 s5, s45, 0
	global_load_lds_dwordx4 v224, s[4:5]
	s_add_u32 m0, s52, 0x5000
	s_add_u32 s4, s44, 0x55000
	s_addc_u32 s5, s45, 0
	global_load_lds_dwordx4 v224, s[4:5]
	s_add_u32 m0, s52, 0x6000
	s_add_u32 s4, s44, 0x66000
	s_addc_u32 s5, s45, 0
	global_load_lds_dwordx4 v224, s[4:5]
	s_add_u32 m0, s52, 0x7000
	s_add_u32 s4, s44, 0x77000
	s_addc_u32 s5, s45, 0
	global_load_lds_dwordx4 v224, s[4:5]
	s_add_u32 m0, s52, 0x8000
	s_add_u32 s4, s46, 0x0
	s_addc_u32 s5, s47, 0
	global_load_lds_dwordx4 v168, s[4:5]
	s_add_u32 m0, s52, 0x9000
	s_add_u32 s4, s46, 0x11000
	s_addc_u32 s5, s47, 0
	global_load_lds_dwordx4 v168, s[4:5]
	s_add_u32 s44, s44, 0x80
	s_addc_u32 s45, s45, 0
	s_add_u32 s46, s46, 0x80
	s_addc_u32 s47, s47, 0
	v_mfma_f32_16x16x32_bf16 v[0:3], v[136:139], a[0:3], v[0:3]
	v_mfma_f32_16x16x32_bf16 v[4:7], v[136:139], a[4:7], v[4:7]
	v_mfma_f32_16x16x32_bf16 v[8:11], v[136:139], a[8:11], v[8:11]
	v_mfma_f32_16x16x32_bf16 v[12:15], v[136:139], a[12:15], v[12:15]
	v_mfma_f32_16x16x32_bf16 v[16:19], v[140:143], a[0:3], v[16:19]
	v_mfma_f32_16x16x32_bf16 v[20:23], v[140:143], a[4:7], v[20:23]
	v_mfma_f32_16x16x32_bf16 v[24:27], v[140:143], a[8:11], v[24:27]
	v_mfma_f32_16x16x32_bf16 v[28:31], v[140:143], a[12:15], v[28:31]
	v_mfma_f32_16x16x32_bf16 v[32:35], v[144:147], a[0:3], v[32:35]
	v_mfma_f32_16x16x32_bf16 v[36:39], v[144:147], a[4:7], v[36:39]
	v_mfma_f32_16x16x32_bf16 v[40:43], v[144:147], a[8:11], v[40:43]
	v_mfma_f32_16x16x32_bf16 v[44:47], v[144:147], a[12:15], v[44:47]
	v_mfma_f32_16x16x32_bf16 v[48:51], v[148:151], a[0:3], v[48:51]
	v_mfma_f32_16x16x32_bf16 v[52:55], v[148:151], a[4:7], v[52:55]
	v_mfma_f32_16x16x32_bf16 v[56:59], v[148:151], a[8:11], v[56:59]
	v_mfma_f32_16x16x32_bf16 v[60:63], v[148:151], a[12:15], v[60:63]
	s_add_u32 s53, s53, 1
	s_branch .Lfh_k
.Lfh_last:
	v_mfma_f32_16x16x32_bf16 v[0:3], v[136:139], a[0:3], v[0:3]
	v_mfma_f32_16x16x32_bf16 v[4:7], v[136:139], a[4:7], v[4:7]
	v_mfma_f32_16x16x32_bf16 v[8:11], v[136:139], a[8:11], v[8:11]
	v_mfma_f32_16x16x32_bf16 v[12:15], v[136:139], a[12:15], v[12:15]
	v_mfma_f32_16x16x32_bf16 v[16:19], v[140:143], a[0:3], v[16:19]
	v_mfma_f32_16x16x32_bf16 v[20:23], v[140:143], a[4:7], v[20:23]
	v_mfma_f32_16x16x32_bf16 v[24:27], v[140:143], a[8:11], v[24:27]
	v_mfma_f32_16x16x32_bf16 v[28:31], v[140:143], a[12:15], v[28:31]
	v_mfma_f32_16x16x32_bf16 v[32:35], v[144:147], a[0:3], v[32:35]
	v_mfma_f32_16x16x32_bf16 v[36:39], v[144:147], a[4:7], v[36:39]
	v_mfma_f32_16x16x32_bf16 v[40:43], v[144:147], a[8:11], v[40:43]
	v_mfma_f32_16x16x32_bf16 v[44:47], v[144:147], a[12:15], v[44:47]
	v_mfma_f32_16x16x32_bf16 v[48:51], v[148:151], a[0:3], v[48:51]
	v_mfma_f32_16x16x32_bf16 v[52:55], v[148:151], a[4:7], v[52:55]
	v_mfma_f32_16x16x32_bf16 v[56:59], v[148:151], a[8:11], v[56:59]
	v_mfma_f32_16x16x32_bf16 v[60:63], v[148:151], a[12:15], v[60:63]
	s_nop 7
	s_nop 7
	v_mov_b32_e32 v226, s50
	v_mov_b32_e32 v227, s51
	v_add_co_u32_e32 v226, vcc, v226, v225
	s_nop 1
	v_addc_co_u32_e32 v227, vcc, 0, v227, vcc
	v_mul_f32_e32 v228, 0xbfb8aa3b, v0
	v_exp_f32_e32 v228, v228
	s_nop 0
	v_add_f32_e32 v229, 1.0, v228
	v_div_scale_f32 v230, s[4:5], v229, v229, v0
	v_rcp_f32_e32 v231, v230
	v_div_scale_f32 v232, vcc, v0, v229, v0
	v_fma_f32 v131, -v230, v231, 1.0
	v_fmac_f32_e32 v231, v131, v231
	v_mul_f32_e32 v233, v232, v231
	v_fma_f32 v131, -v230, v233, v232
	v_fmac_f32_e32 v233, v131, v231
	v_fma_f32 v230, -v230, v233, v232
	v_div_fmas_f32 v230, v230, v231, v233
	v_div_fixup_f32 v135, v230, v229, v0
	v_mul_f32_e32 v135, v8, v135
	v_mul_f32_e32 v228, 0xbfb8aa3b, v4
	v_exp_f32_e32 v228, v228
	s_nop 0
	v_add_f32_e32 v229, 1.0, v228
	v_div_scale_f32 v230, s[4:5], v229, v229, v4
	v_rcp_f32_e32 v231, v230
	v_div_scale_f32 v232, vcc, v4, v229, v4
	v_fma_f32 v131, -v230, v231, 1.0
	v_fmac_f32_e32 v231, v131, v231
	v_mul_f32_e32 v233, v232, v231
	v_fma_f32 v131, -v230, v233, v232
	v_fmac_f32_e32 v233, v131, v231
	v_fma_f32 v230, -v230, v233, v232
	v_div_fmas_f32 v230, v230, v231, v233
	v_div_fixup_f32 v133, v230, v229, v4
	v_mul_f32_e32 v133, v12, v133
	v_cvt_pk_bf16_f32 v133, v135, v133
	global_store_dword v[226:227], v133, off
	s_mov_b64 s[40:41], 0x1680
	v_lshl_add_u64 v[226:227], v[226:227], 0, s[40:41]
	v_mul_f32_e32 v228, 0xbfb8aa3b, v1
	v_exp_f32_e32 v228, v228
	s_nop 0
	v_add_f32_e32 v229, 1.0, v228
	v_div_scale_f32 v230, s[4:5], v229, v229, v1
	v_rcp_f32_e32 v231, v230
	v_div_scale_f32 v232, vcc, v1, v229, v1
	v_fma_f32 v131, -v230, v231, 1.0
	v_fmac_f32_e32 v231, v131, v231
	v_mul_f32_e32 v233, v232, v231
	v_fma_f32 v131, -v230, v233, v232
	v_fmac_f32_e32 v233, v131, v231
	v_fma_f32 v230, -v230, v233, v232
	v_div_fmas_f32 v230, v230, v231, v233
	v_div_fixup_f32 v135, v230, v229, v1
	v_mul_f32_e32 v135, v9, v135
	v_mul_f32_e32 v228, 0xbfb8aa3b, v5
	v_exp_f32_e32 v228, v228
	s_nop 0
	v_add_f32_e32 v229, 1.0, v228
	v_div_scale_f32 v230, s[4:5], v229, v229, v5
	v_rcp_f32_e32 v231, v230
	v_div_scale_f32 v232, vcc, v5, v229, v5
	v_fma_f32 v131, -v230, v231, 1.0
	v_fmac_f32_e32 v231, v131, v231
	v_mul_f32_e32 v233, v232, v231
	v_fma_f32 v131, -v230, v233, v232
	v_fmac_f32_e32 v233, v131, v231
	v_fma_f32 v230, -v230, v233, v232
	v_div_fmas_f32 v230, v230, v231, v233
	v_div_fixup_f32 v133, v230, v229, v5
	v_mul_f32_e32 v133, v13, v133
	v_cvt_pk_bf16_f32 v133, v135, v133
	global_store_dword v[226:227], v133, off
	s_mov_b64 s[40:41], 0x1680
	v_lshl_add_u64 v[226:227], v[226:227], 0, s[40:41]
	v_mul_f32_e32 v228, 0xbfb8aa3b, v2
	v_exp_f32_e32 v228, v228
	s_nop 0
	v_add_f32_e32 v229, 1.0, v228
	v_div_scale_f32 v230, s[4:5], v229, v229, v2
	v_rcp_f32_e32 v231, v230
	v_div_scale_f32 v232, vcc, v2, v229, v2
	v_fma_f32 v131, -v230, v231, 1.0
	v_fmac_f32_e32 v231, v131, v231
	v_mul_f32_e32 v233, v232, v231
	v_fma_f32 v131, -v230, v233, v232
	v_fmac_f32_e32 v233, v131, v231
	v_fma_f32 v230, -v230, v233, v232
	v_div_fmas_f32 v230, v230, v231, v233
	v_div_fixup_f32 v135, v230, v229, v2
	v_mul_f32_e32 v135, v10, v135
	v_mul_f32_e32 v228, 0xbfb8aa3b, v6
	v_exp_f32_e32 v228, v228
	s_nop 0
	v_add_f32_e32 v229, 1.0, v228
	v_div_scale_f32 v230, s[4:5], v229, v229, v6
	v_rcp_f32_e32 v231, v230
	v_div_scale_f32 v232, vcc, v6, v229, v6
	v_fma_f32 v131, -v230, v231, 1.0
	v_fmac_f32_e32 v231, v131, v231
	v_mul_f32_e32 v233, v232, v231
	v_fma_f32 v131, -v230, v233, v232
	v_fmac_f32_e32 v233, v131, v231
	v_fma_f32 v230, -v230, v233, v232
	v_div_fmas_f32 v230, v230, v231, v233
	v_div_fixup_f32 v133, v230, v229, v6
	v_mul_f32_e32 v133, v14, v133
	v_cvt_pk_bf16_f32 v133, v135, v133
	global_store_dword v[226:227], v133, off
	s_mov_b64 s[40:41], 0x1680
	v_lshl_add_u64 v[226:227], v[226:227], 0, s[40:41]
	v_mul_f32_e32 v228, 0xbfb8aa3b, v3
	v_exp_f32_e32 v228, v228
	s_nop 0
	v_add_f32_e32 v229, 1.0, v228
	v_div_scale_f32 v230, s[4:5], v229, v229, v3
	v_rcp_f32_e32 v231, v230
	v_div_scale_f32 v232, vcc, v3, v229, v3
	v_fma_f32 v131, -v230, v231, 1.0
	v_fmac_f32_e32 v231, v131, v231
	v_mul_f32_e32 v233, v232, v231
	v_fma_f32 v131, -v230, v233, v232
	v_fmac_f32_e32 v233, v131, v231
	v_fma_f32 v230, -v230, v233, v232
	v_div_fmas_f32 v230, v230, v231, v233
	v_div_fixup_f32 v135, v230, v229, v3
	v_mul_f32_e32 v135, v11, v135
	v_mul_f32_e32 v228, 0xbfb8aa3b, v7
	v_exp_f32_e32 v228, v228
	s_nop 0
	v_add_f32_e32 v229, 1.0, v228
	v_div_scale_f32 v230, s[4:5], v229, v229, v7
	v_rcp_f32_e32 v231, v230
	v_div_scale_f32 v232, vcc, v7, v229, v7
	v_fma_f32 v131, -v230, v231, 1.0
	v_fmac_f32_e32 v231, v131, v231
	v_mul_f32_e32 v233, v232, v231
	v_fma_f32 v131, -v230, v233, v232
	v_fmac_f32_e32 v233, v131, v231
	v_fma_f32 v230, -v230, v233, v232
	v_div_fmas_f32 v230, v230, v231, v233
	v_div_fixup_f32 v133, v230, v229, v7
	v_mul_f32_e32 v133, v15, v133
	v_cvt_pk_bf16_f32 v133, v135, v133
	global_store_dword v[226:227], v133, off
	s_mov_b64 s[40:41], 0x12480
	v_lshl_add_u64 v[226:227], v[226:227], 0, s[40:41]
	v_mul_f32_e32 v228, 0xbfb8aa3b, v16
	v_exp_f32_e32 v228, v228
	s_nop 0
	v_add_f32_e32 v229, 1.0, v228
	v_div_scale_f32 v230, s[4:5], v229, v229, v16
	v_rcp_f32_e32 v231, v230
	v_div_scale_f32 v232, vcc, v16, v229, v16
	v_fma_f32 v131, -v230, v231, 1.0
	v_fmac_f32_e32 v231, v131, v231
	v_mul_f32_e32 v233, v232, v231
	v_fma_f32 v131, -v230, v233, v232
	v_fmac_f32_e32 v233, v131, v231
	v_fma_f32 v230, -v230, v233, v232
	v_div_fmas_f32 v230, v230, v231, v233
	v_div_fixup_f32 v135, v230, v229, v16
	v_mul_f32_e32 v135, v24, v135
	v_mul_f32_e32 v228, 0xbfb8aa3b, v20
	v_exp_f32_e32 v228, v228
	s_nop 0
	v_add_f32_e32 v229, 1.0, v228
	v_div_scale_f32 v230, s[4:5], v229, v229, v20
	v_rcp_f32_e32 v231, v230
	v_div_scale_f32 v232, vcc, v20, v229, v20
	v_fma_f32 v131, -v230, v231, 1.0
	v_fmac_f32_e32 v231, v131, v231
	v_mul_f32_e32 v233, v232, v231
	v_fma_f32 v131, -v230, v233, v232
	v_fmac_f32_e32 v233, v131, v231
	v_fma_f32 v230, -v230, v233, v232
	v_div_fmas_f32 v230, v230, v231, v233
	v_div_fixup_f32 v133, v230, v229, v20
	v_mul_f32_e32 v133, v28, v133
	v_cvt_pk_bf16_f32 v133, v135, v133
	global_store_dword v[226:227], v133, off
	s_mov_b64 s[40:41], 0x1680
	v_lshl_add_u64 v[226:227], v[226:227], 0, s[40:41]
	v_mul_f32_e32 v228, 0xbfb8aa3b, v17
	v_exp_f32_e32 v228, v228
	s_nop 0
	v_add_f32_e32 v229, 1.0, v228
	v_div_scale_f32 v230, s[4:5], v229, v229, v17
	v_rcp_f32_e32 v231, v230
	v_div_scale_f32 v232, vcc, v17, v229, v17
	v_fma_f32 v131, -v230, v231, 1.0
	v_fmac_f32_e32 v231, v131, v231
	v_mul_f32_e32 v233, v232, v231
	v_fma_f32 v131, -v230, v233, v232
	v_fmac_f32_e32 v233, v131, v231
	v_fma_f32 v230, -v230, v233, v232
	v_div_fmas_f32 v230, v230, v231, v233
	v_div_fixup_f32 v135, v230, v229, v17
	v_mul_f32_e32 v135, v25, v135
	v_mul_f32_e32 v228, 0xbfb8aa3b, v21
	v_exp_f32_e32 v228, v228
	s_nop 0
	v_add_f32_e32 v229, 1.0, v228
	v_div_scale_f32 v230, s[4:5], v229, v229, v21
	v_rcp_f32_e32 v231, v230
	v_div_scale_f32 v232, vcc, v21, v229, v21
	v_fma_f32 v131, -v230, v231, 1.0
	v_fmac_f32_e32 v231, v131, v231
	v_mul_f32_e32 v233, v232, v231
	v_fma_f32 v131, -v230, v233, v232
	v_fmac_f32_e32 v233, v131, v231
	v_fma_f32 v230, -v230, v233, v232
	v_div_fmas_f32 v230, v230, v231, v233
	v_div_fixup_f32 v133, v230, v229, v21
	v_mul_f32_e32 v133, v29, v133
	v_cvt_pk_bf16_f32 v133, v135, v133
	global_store_dword v[226:227], v133, off
	s_mov_b64 s[40:41], 0x1680
	v_lshl_add_u64 v[226:227], v[226:227], 0, s[40:41]
	v_mul_f32_e32 v228, 0xbfb8aa3b, v18
	v_exp_f32_e32 v228, v228
	s_nop 0
	v_add_f32_e32 v229, 1.0, v228
	v_div_scale_f32 v230, s[4:5], v229, v229, v18
	v_rcp_f32_e32 v231, v230
	v_div_scale_f32 v232, vcc, v18, v229, v18
	v_fma_f32 v131, -v230, v231, 1.0
	v_fmac_f32_e32 v231, v131, v231
	v_mul_f32_e32 v233, v232, v231
	v_fma_f32 v131, -v230, v233, v232
	v_fmac_f32_e32 v233, v131, v231
	v_fma_f32 v230, -v230, v233, v232
	v_div_fmas_f32 v230, v230, v231, v233
	v_div_fixup_f32 v135, v230, v229, v18
	v_mul_f32_e32 v135, v26, v135
	v_mul_f32_e32 v228, 0xbfb8aa3b, v22
	v_exp_f32_e32 v228, v228
	s_nop 0
	v_add_f32_e32 v229, 1.0, v228
	v_div_scale_f32 v230, s[4:5], v229, v229, v22
	v_rcp_f32_e32 v231, v230
	v_div_scale_f32 v232, vcc, v22, v229, v22
	v_fma_f32 v131, -v230, v231, 1.0
	v_fmac_f32_e32 v231, v131, v231
	v_mul_f32_e32 v233, v232, v231
	v_fma_f32 v131, -v230, v233, v232
	v_fmac_f32_e32 v233, v131, v231
	v_fma_f32 v230, -v230, v233, v232
	v_div_fmas_f32 v230, v230, v231, v233
	v_div_fixup_f32 v133, v230, v229, v22
	v_mul_f32_e32 v133, v30, v133
	v_cvt_pk_bf16_f32 v133, v135, v133
	global_store_dword v[226:227], v133, off
	s_mov_b64 s[40:41], 0x1680
	v_lshl_add_u64 v[226:227], v[226:227], 0, s[40:41]
	v_mul_f32_e32 v228, 0xbfb8aa3b, v19
	v_exp_f32_e32 v228, v228
	s_nop 0
	v_add_f32_e32 v229, 1.0, v228
	v_div_scale_f32 v230, s[4:5], v229, v229, v19
	v_rcp_f32_e32 v231, v230
	v_div_scale_f32 v232, vcc, v19, v229, v19
	v_fma_f32 v131, -v230, v231, 1.0
	v_fmac_f32_e32 v231, v131, v231
	v_mul_f32_e32 v233, v232, v231
	v_fma_f32 v131, -v230, v233, v232
	v_fmac_f32_e32 v233, v131, v231
	v_fma_f32 v230, -v230, v233, v232
	v_div_fmas_f32 v230, v230, v231, v233
	v_div_fixup_f32 v135, v230, v229, v19
	v_mul_f32_e32 v135, v27, v135
	v_mul_f32_e32 v228, 0xbfb8aa3b, v23
	v_exp_f32_e32 v228, v228
	s_nop 0
	v_add_f32_e32 v229, 1.0, v228
	v_div_scale_f32 v230, s[4:5], v229, v229, v23
	v_rcp_f32_e32 v231, v230
	v_div_scale_f32 v232, vcc, v23, v229, v23
	v_fma_f32 v131, -v230, v231, 1.0
	v_fmac_f32_e32 v231, v131, v231
	v_mul_f32_e32 v233, v232, v231
	v_fma_f32 v131, -v230, v233, v232
	v_fmac_f32_e32 v233, v131, v231
	v_fma_f32 v230, -v230, v233, v232
	v_div_fmas_f32 v230, v230, v231, v233
	v_div_fixup_f32 v133, v230, v229, v23
	v_mul_f32_e32 v133, v31, v133
	v_cvt_pk_bf16_f32 v133, v135, v133
	global_store_dword v[226:227], v133, off
	s_mov_b64 s[40:41], 0x12480
	v_lshl_add_u64 v[226:227], v[226:227], 0, s[40:41]
	v_mul_f32_e32 v228, 0xbfb8aa3b, v32
	v_exp_f32_e32 v228, v228
	s_nop 0
	v_add_f32_e32 v229, 1.0, v228
	v_div_scale_f32 v230, s[4:5], v229, v229, v32
	v_rcp_f32_e32 v231, v230
	v_div_scale_f32 v232, vcc, v32, v229, v32
	v_fma_f32 v131, -v230, v231, 1.0
	v_fmac_f32_e32 v231, v131, v231
	v_mul_f32_e32 v233, v232, v231
	v_fma_f32 v131, -v230, v233, v232
	v_fmac_f32_e32 v233, v131, v231
	v_fma_f32 v230, -v230, v233, v232
	v_div_fmas_f32 v230, v230, v231, v233
	v_div_fixup_f32 v135, v230, v229, v32
	v_mul_f32_e32 v135, v40, v135
	v_mul_f32_e32 v228, 0xbfb8aa3b, v36
	v_exp_f32_e32 v228, v228
	s_nop 0
	v_add_f32_e32 v229, 1.0, v228
	v_div_scale_f32 v230, s[4:5], v229, v229, v36
	v_rcp_f32_e32 v231, v230
	v_div_scale_f32 v232, vcc, v36, v229, v36
	v_fma_f32 v131, -v230, v231, 1.0
	v_fmac_f32_e32 v231, v131, v231
	v_mul_f32_e32 v233, v232, v231
	v_fma_f32 v131, -v230, v233, v232
	v_fmac_f32_e32 v233, v131, v231
	v_fma_f32 v230, -v230, v233, v232
	v_div_fmas_f32 v230, v230, v231, v233
	v_div_fixup_f32 v133, v230, v229, v36
	v_mul_f32_e32 v133, v44, v133
	v_cvt_pk_bf16_f32 v133, v135, v133
	global_store_dword v[226:227], v133, off
	s_mov_b64 s[40:41], 0x1680
	v_lshl_add_u64 v[226:227], v[226:227], 0, s[40:41]
	v_mul_f32_e32 v228, 0xbfb8aa3b, v33
	v_exp_f32_e32 v228, v228
	s_nop 0
	v_add_f32_e32 v229, 1.0, v228
	v_div_scale_f32 v230, s[4:5], v229, v229, v33
	v_rcp_f32_e32 v231, v230
	v_div_scale_f32 v232, vcc, v33, v229, v33
	v_fma_f32 v131, -v230, v231, 1.0
	v_fmac_f32_e32 v231, v131, v231
	v_mul_f32_e32 v233, v232, v231
	v_fma_f32 v131, -v230, v233, v232
	v_fmac_f32_e32 v233, v131, v231
	v_fma_f32 v230, -v230, v233, v232
	v_div_fmas_f32 v230, v230, v231, v233
	v_div_fixup_f32 v135, v230, v229, v33
	v_mul_f32_e32 v135, v41, v135
	v_mul_f32_e32 v228, 0xbfb8aa3b, v37
	v_exp_f32_e32 v228, v228
	s_nop 0
	v_add_f32_e32 v229, 1.0, v228
	v_div_scale_f32 v230, s[4:5], v229, v229, v37
	v_rcp_f32_e32 v231, v230
	v_div_scale_f32 v232, vcc, v37, v229, v37
	v_fma_f32 v131, -v230, v231, 1.0
	v_fmac_f32_e32 v231, v131, v231
	v_mul_f32_e32 v233, v232, v231
	v_fma_f32 v131, -v230, v233, v232
	v_fmac_f32_e32 v233, v131, v231
	v_fma_f32 v230, -v230, v233, v232
	v_div_fmas_f32 v230, v230, v231, v233
	v_div_fixup_f32 v133, v230, v229, v37
	v_mul_f32_e32 v133, v45, v133
	v_cvt_pk_bf16_f32 v133, v135, v133
	global_store_dword v[226:227], v133, off
	s_mov_b64 s[40:41], 0x1680
	v_lshl_add_u64 v[226:227], v[226:227], 0, s[40:41]
	v_mul_f32_e32 v228, 0xbfb8aa3b, v34
	v_exp_f32_e32 v228, v228
	s_nop 0
	v_add_f32_e32 v229, 1.0, v228
	v_div_scale_f32 v230, s[4:5], v229, v229, v34
	v_rcp_f32_e32 v231, v230
	v_div_scale_f32 v232, vcc, v34, v229, v34
	v_fma_f32 v131, -v230, v231, 1.0
	v_fmac_f32_e32 v231, v131, v231
	v_mul_f32_e32 v233, v232, v231
	v_fma_f32 v131, -v230, v233, v232
	v_fmac_f32_e32 v233, v131, v231
	v_fma_f32 v230, -v230, v233, v232
	v_div_fmas_f32 v230, v230, v231, v233
	v_div_fixup_f32 v135, v230, v229, v34
	v_mul_f32_e32 v135, v42, v135
	v_mul_f32_e32 v228, 0xbfb8aa3b, v38
	v_exp_f32_e32 v228, v228
	s_nop 0
	v_add_f32_e32 v229, 1.0, v228
	v_div_scale_f32 v230, s[4:5], v229, v229, v38
	v_rcp_f32_e32 v231, v230
	v_div_scale_f32 v232, vcc, v38, v229, v38
	v_fma_f32 v131, -v230, v231, 1.0
	v_fmac_f32_e32 v231, v131, v231
	v_mul_f32_e32 v233, v232, v231
	v_fma_f32 v131, -v230, v233, v232
	v_fmac_f32_e32 v233, v131, v231
	v_fma_f32 v230, -v230, v233, v232
	v_div_fmas_f32 v230, v230, v231, v233
	v_div_fixup_f32 v133, v230, v229, v38
	v_mul_f32_e32 v133, v46, v133
	v_cvt_pk_bf16_f32 v133, v135, v133
	global_store_dword v[226:227], v133, off
	s_mov_b64 s[40:41], 0x1680
	v_lshl_add_u64 v[226:227], v[226:227], 0, s[40:41]
	v_mul_f32_e32 v228, 0xbfb8aa3b, v35
	v_exp_f32_e32 v228, v228
	s_nop 0
	v_add_f32_e32 v229, 1.0, v228
	v_div_scale_f32 v230, s[4:5], v229, v229, v35
	v_rcp_f32_e32 v231, v230
	v_div_scale_f32 v232, vcc, v35, v229, v35
	v_fma_f32 v131, -v230, v231, 1.0
	v_fmac_f32_e32 v231, v131, v231
	v_mul_f32_e32 v233, v232, v231
	v_fma_f32 v131, -v230, v233, v232
	v_fmac_f32_e32 v233, v131, v231
	v_fma_f32 v230, -v230, v233, v232
	v_div_fmas_f32 v230, v230, v231, v233
	v_div_fixup_f32 v135, v230, v229, v35
	v_mul_f32_e32 v135, v43, v135
	v_mul_f32_e32 v228, 0xbfb8aa3b, v39
	v_exp_f32_e32 v228, v228
	s_nop 0
	v_add_f32_e32 v229, 1.0, v228
	v_div_scale_f32 v230, s[4:5], v229, v229, v39
	v_rcp_f32_e32 v231, v230
	v_div_scale_f32 v232, vcc, v39, v229, v39
	v_fma_f32 v131, -v230, v231, 1.0
	v_fmac_f32_e32 v231, v131, v231
	v_mul_f32_e32 v233, v232, v231
	v_fma_f32 v131, -v230, v233, v232
	v_fmac_f32_e32 v233, v131, v231
	v_fma_f32 v230, -v230, v233, v232
	v_div_fmas_f32 v230, v230, v231, v233
	v_div_fixup_f32 v133, v230, v229, v39
	v_mul_f32_e32 v133, v47, v133
	v_cvt_pk_bf16_f32 v133, v135, v133
	global_store_dword v[226:227], v133, off
	s_mov_b64 s[40:41], 0x12480
	v_lshl_add_u64 v[226:227], v[226:227], 0, s[40:41]
	v_mul_f32_e32 v228, 0xbfb8aa3b, v48
	v_exp_f32_e32 v228, v228
	s_nop 0
	v_add_f32_e32 v229, 1.0, v228
	v_div_scale_f32 v230, s[4:5], v229, v229, v48
	v_rcp_f32_e32 v231, v230
	v_div_scale_f32 v232, vcc, v48, v229, v48
	v_fma_f32 v131, -v230, v231, 1.0
	v_fmac_f32_e32 v231, v131, v231
	v_mul_f32_e32 v233, v232, v231
	v_fma_f32 v131, -v230, v233, v232
	v_fmac_f32_e32 v233, v131, v231
	v_fma_f32 v230, -v230, v233, v232
	v_div_fmas_f32 v230, v230, v231, v233
	v_div_fixup_f32 v135, v230, v229, v48
	v_mul_f32_e32 v135, v56, v135
	v_mul_f32_e32 v228, 0xbfb8aa3b, v52
	v_exp_f32_e32 v228, v228
	s_nop 0
	v_add_f32_e32 v229, 1.0, v228
	v_div_scale_f32 v230, s[4:5], v229, v229, v52
	v_rcp_f32_e32 v231, v230
	v_div_scale_f32 v232, vcc, v52, v229, v52
	v_fma_f32 v131, -v230, v231, 1.0
	v_fmac_f32_e32 v231, v131, v231
	v_mul_f32_e32 v233, v232, v231
	v_fma_f32 v131, -v230, v233, v232
	v_fmac_f32_e32 v233, v131, v231
	v_fma_f32 v230, -v230, v233, v232
	v_div_fmas_f32 v230, v230, v231, v233
	v_div_fixup_f32 v133, v230, v229, v52
	v_mul_f32_e32 v133, v60, v133
	v_cvt_pk_bf16_f32 v133, v135, v133
	global_store_dword v[226:227], v133, off
	s_mov_b64 s[40:41], 0x1680
	v_lshl_add_u64 v[226:227], v[226:227], 0, s[40:41]
	v_mul_f32_e32 v228, 0xbfb8aa3b, v49
	v_exp_f32_e32 v228, v228
	s_nop 0
	v_add_f32_e32 v229, 1.0, v228
	v_div_scale_f32 v230, s[4:5], v229, v229, v49
	v_rcp_f32_e32 v231, v230
	v_div_scale_f32 v232, vcc, v49, v229, v49
	v_fma_f32 v131, -v230, v231, 1.0
	v_fmac_f32_e32 v231, v131, v231
	v_mul_f32_e32 v233, v232, v231
	v_fma_f32 v131, -v230, v233, v232
	v_fmac_f32_e32 v233, v131, v231
	v_fma_f32 v230, -v230, v233, v232
	v_div_fmas_f32 v230, v230, v231, v233
	v_div_fixup_f32 v135, v230, v229, v49
	v_mul_f32_e32 v135, v57, v135
	v_mul_f32_e32 v228, 0xbfb8aa3b, v53
	v_exp_f32_e32 v228, v228
	s_nop 0
	v_add_f32_e32 v229, 1.0, v228
	v_div_scale_f32 v230, s[4:5], v229, v229, v53
	v_rcp_f32_e32 v231, v230
	v_div_scale_f32 v232, vcc, v53, v229, v53
	v_fma_f32 v131, -v230, v231, 1.0
	v_fmac_f32_e32 v231, v131, v231
	v_mul_f32_e32 v233, v232, v231
	v_fma_f32 v131, -v230, v233, v232
	v_fmac_f32_e32 v233, v131, v231
	v_fma_f32 v230, -v230, v233, v232
	v_div_fmas_f32 v230, v230, v231, v233
	v_div_fixup_f32 v133, v230, v229, v53
	v_mul_f32_e32 v133, v61, v133
	v_cvt_pk_bf16_f32 v133, v135, v133
	global_store_dword v[226:227], v133, off
	s_mov_b64 s[40:41], 0x1680
	v_lshl_add_u64 v[226:227], v[226:227], 0, s[40:41]
	v_mul_f32_e32 v228, 0xbfb8aa3b, v50
	v_exp_f32_e32 v228, v228
	s_nop 0
	v_add_f32_e32 v229, 1.0, v228
	v_div_scale_f32 v230, s[4:5], v229, v229, v50
	v_rcp_f32_e32 v231, v230
	v_div_scale_f32 v232, vcc, v50, v229, v50
	v_fma_f32 v131, -v230, v231, 1.0
	v_fmac_f32_e32 v231, v131, v231
	v_mul_f32_e32 v233, v232, v231
	v_fma_f32 v131, -v230, v233, v232
	v_fmac_f32_e32 v233, v131, v231
	v_fma_f32 v230, -v230, v233, v232
	v_div_fmas_f32 v230, v230, v231, v233
	v_div_fixup_f32 v135, v230, v229, v50
	v_mul_f32_e32 v135, v58, v135
	v_mul_f32_e32 v228, 0xbfb8aa3b, v54
	v_exp_f32_e32 v228, v228
	s_nop 0
	v_add_f32_e32 v229, 1.0, v228
	v_div_scale_f32 v230, s[4:5], v229, v229, v54
	v_rcp_f32_e32 v231, v230
	v_div_scale_f32 v232, vcc, v54, v229, v54
	v_fma_f32 v131, -v230, v231, 1.0
	v_fmac_f32_e32 v231, v131, v231
	v_mul_f32_e32 v233, v232, v231
	v_fma_f32 v131, -v230, v233, v232
	v_fmac_f32_e32 v233, v131, v231
	v_fma_f32 v230, -v230, v233, v232
	v_div_fmas_f32 v230, v230, v231, v233
	v_div_fixup_f32 v133, v230, v229, v54
	v_mul_f32_e32 v133, v62, v133
	v_cvt_pk_bf16_f32 v133, v135, v133
	global_store_dword v[226:227], v133, off
	s_mov_b64 s[40:41], 0x1680
	v_lshl_add_u64 v[226:227], v[226:227], 0, s[40:41]
	v_mul_f32_e32 v228, 0xbfb8aa3b, v51
	v_exp_f32_e32 v228, v228
	s_nop 0
	v_add_f32_e32 v229, 1.0, v228
	v_div_scale_f32 v230, s[4:5], v229, v229, v51
	v_rcp_f32_e32 v231, v230
	v_div_scale_f32 v232, vcc, v51, v229, v51
	v_fma_f32 v131, -v230, v231, 1.0
	v_fmac_f32_e32 v231, v131, v231
	v_mul_f32_e32 v233, v232, v231
	v_fma_f32 v131, -v230, v233, v232
	v_fmac_f32_e32 v233, v131, v231
	v_fma_f32 v230, -v230, v233, v232
	v_div_fmas_f32 v230, v230, v231, v233
	v_div_fixup_f32 v135, v230, v229, v51
	v_mul_f32_e32 v135, v59, v135
	v_mul_f32_e32 v228, 0xbfb8aa3b, v55
	v_exp_f32_e32 v228, v228
	s_nop 0
	v_add_f32_e32 v229, 1.0, v228
	v_div_scale_f32 v230, s[4:5], v229, v229, v55
	v_rcp_f32_e32 v231, v230
	v_div_scale_f32 v232, vcc, v55, v229, v55
	v_fma_f32 v131, -v230, v231, 1.0
	v_fmac_f32_e32 v231, v131, v231
	v_mul_f32_e32 v233, v232, v231
	v_fma_f32 v131, -v230, v233, v232
	v_fmac_f32_e32 v233, v131, v231
	v_fma_f32 v230, -v230, v233, v232
	v_div_fmas_f32 v230, v230, v231, v233
	v_div_fixup_f32 v133, v230, v229, v55
	v_mul_f32_e32 v133, v63, v133
	v_cvt_pk_bf16_f32 v133, v135, v133
	global_store_dword v[226:227], v133, off
